# grid barriers: waiting waves 1-7 touch the next 28 KiB of code (PC-relative loads) to warm L2 for the next phase's instruction fetches
# speedup vs baseline: 1.0124x; 1.0074x over previous
; DI int fresh_tid() { int t = threadIdx.x; asm volatile("" : "+v"(t)); return t; }
; DI unsigned xb_ld(unsigned* p)              { return __hip_atomic_load(p, __ATOMIC_RELAXED, __HIP_MEMORY_SCOPE_AGENT); }
; DI unsigned xb_xcc_id() { return (unsigned)__builtin_amdgcn_s_getreg((3 << 11) | 20) & 0xFu; }
; DI void xcd_barrier_complete(unsigned* bar, unsigned x, unsigned& nloc, unsigned& nx) {
;     ...
;     for (;;) {
;         sum = 0u; cnt = 0u; mine = 0u;
; #pragma unroll
;         for (unsigned j = 0; j < 16; ++j) { const unsigned c = xb_ld(&bar[XB_XCNT(j)]); sum += c; cnt += (c > 0u) ? 1u : 0u; mine = (j == x) ? c : mine; }
; DI void xcd_barrier(unsigned* bar, volatile __attribute__((address_space(3))) unsigned* st) {
;     asm volatile("s_waitcnt vmcnt(0)" ::: "memory");
;     __syncthreads();
;     if (fresh_tid() == 0) {
;         __builtin_amdgcn_s_waitcnt(0);
;         const unsigned x = xb_xcc_id();
;         unsigned nloc = st[0], nx = st[1];
;         if (nloc == 0u) { xcd_barrier_complete(bar, x, nloc, nx); st[0] = nloc; st[1] = nx; }
.LBB0_132:
	s_or_b64 exec, exec, s[6:7]
	s_waitcnt vmcnt(0)
	v_mov_b32_e32 v0, v250
	s_barrier
	s_getpc_b64 vcc
	v_mov_b32_e32 v2, vcc_lo
	v_mov_b32_e32 v3, vcc_hi
	v_lshlrev_b32_e32 v1, 6, v0
	v_cmp_lt_u32_e32 vcc, 63, v0
	s_and_saveexec_b64 s[0:1], vcc
	s_cbranch_execz .Lcpf_s1
	v_add_co_u32_e32 v2, vcc, v2, v1
	s_nop 1
	v_addc_co_u32_e32 v3, vcc, 0, v3, vcc
	global_load_dword v4, v[2:3], off
.Lcpf_s1:
	s_or_b64 exec, exec, s[0:1]
	s_nop 0
	v_cmp_eq_u32_e32 vcc, 0, v0
	s_and_saveexec_b64 s[0:1], vcc
	s_cbranch_execz .LBB0_184
	v_mov_b32_e32 v0, 0
	s_waitcnt vmcnt(0) expcnt(0) lgkmcnt(0)
	s_getreg_b32 s3, hwreg(HW_REG_XCC_ID, 0, 4)
	ds_read_b32 v2, v0
	ds_read_b32 v1, v0 offset:4
	s_and_b32 s3, s3, 15
	s_waitcnt lgkmcnt(1)
	v_cmp_ne_u32_e32 vcc, 0, v2
	s_cbranch_vccnz .LBB0_148
	s_add_u32 s4, s70, 0x34e2300
	s_addc_u32 s5, s71, 0
	s_add_u32 s6, s70, 0x34e2500
	s_addc_u32 s7, s71, 0
	s_add_u32 s8, s70, 0x34e2600
	s_addc_u32 s9, s71, 0
	s_add_u32 s10, s70, 0x34e2700
	s_addc_u32 s11, s71, 0
	s_add_u32 s12, s70, 0x34e2800
	s_addc_u32 s13, s71, 0
	s_add_u32 s14, s70, 0x34e2900
	s_addc_u32 s15, s71, 0
	s_add_u32 s16, s70, 0x34e2a00
	s_addc_u32 s17, s71, 0
	s_add_u32 s20, s70, 0x34e2b00
	s_addc_u32 s21, s71, 0
	s_add_u32 s22, s70, 0x34e2c00
	s_addc_u32 s23, s71, 0
	s_add_u32 s24, s70, 0x34e2d00
	s_addc_u32 s25, s71, 0
	s_add_u32 s26, s70, 0x34e2e00
	s_addc_u32 s27, s71, 0
	s_add_u32 s28, s70, 0x34e2f00
	s_addc_u32 s29, s71, 0
	s_add_u32 s30, s70, 0x34e3000
	s_addc_u32 s31, s71, 0
	s_add_u32 s34, s70, 0x34e3100
	s_addc_u32 s35, s71, 0
	s_add_u32 s36, s70, 0x34e3200
	s_addc_u32 s37, s71, 0
	s_add_u32 s38, s70, 0x34e3300
	s_addc_u32 s39, s71, 0
	s_add_u32 s40, s70, 0x34e3400
	s_addc_u32 s41, s71, 0
	s_mov_b32 s48, 1
	s_branch .LBB0_136

; DI void phase1(const Params& p, unsigned char* smem) {
;     ...
;     bf16_t* h1 = (bf16_t*)(ws + 1 * U_);
;     float4 gw0[16], gw1[16];
; #pragma unroll
;     for (int i = 0; i < 4; ++i)
; #pragma unroll
;         for (int e = 0; e < 4; ++e) {
;             const float* wp = p.in[4] + (size_t)(i * 256 + lane * 4 + e) * 4616 + 2048;
;             gw0[i * 4 + e] = *(const float4*)wp; gw1[i * 4 + e] = *(const float4*)(wp + 4);
;         }
;     float* ig = (float*)(ws + OFF_IG);
;     float* lf = (float*)(ws + OFF_LOGF);
;     for (int row0 = (blockIdx.x * 8 + wid) * 4; row0 < T_; row0 += gridDim.x * 32) {
.LBB0_184:
	s_or_b64 exec, exec, s[0:1]
	s_add_u32 s62, s70, 0x2000000
	s_addc_u32 s63, s71, 0
	s_add_u32 s94, s70, 0x4000000
	s_addc_u32 s95, s71, 0
	s_add_u32 s88, s70, 0x325c000
	v_mov_b32_e32 v0, v250
	s_addc_u32 s89, s71, 0
	s_waitcnt lgkmcnt(0)
	s_waitcnt vmcnt(0)
	s_barrier
	v_lshlrev_b32_e32 v150, 4, v250
	v_add_u32_e32 v151, 0x6000, v150
	v_add_u32_e32 v152, 0xc000, v150
	v_add_u32_e32 v153, 0x12000, v150
	global_load_dwordx4 v[156:159], v150, s[62:63]
	global_load_dwordx4 v[160:163], v151, s[62:63]
	global_load_dwordx4 v[164:167], v152, s[62:63]
	global_load_dwordx4 v[168:171], v153, s[62:63]
	s_waitcnt vmcnt(3)
	ds_write_b128 v150, v[156:159] offset:1024
	s_waitcnt vmcnt(2)
	ds_write_b128 v150, v[160:163] offset:9216
	s_waitcnt vmcnt(1)
	ds_write_b128 v150, v[164:167] offset:17408
	s_waitcnt vmcnt(0)
	ds_write_b128 v150, v[168:171] offset:25600
	s_waitcnt lgkmcnt(0)
	s_barrier
	s_add_u32 s20, s70, 0x32dc000
	v_ashrrev_i32_e32 v1, 4, v0
	s_addc_u32 s21, s71, 0
	s_lshl_b32 s0, s2, 5
	v_and_b32_e32 v1, -4, v1
	v_writelane_b32 v254, s0, 52
	v_add_u32_e32 v176, s0, v1
	s_mov_b32 s0, 0x8000
	v_cmp_gt_i32_e32 vcc, s0, v176
	s_and_saveexec_b64 s[22:23], vcc
	s_cbranch_execz .LBB0_219
	v_and_b32_e32 v230, 63, v0
	v_readfirstlane_b32 s4, v0
	v_readlane_b32 s36, v254, 4
	v_mov_b32_e32 v179, 0
	v_readlane_b32 s44, v254, 12
	v_readlane_b32 s45, v254, 13
	s_lshr_b32 s4, s4, 6
	s_lshr_b32 s5, s4, 1
	s_and_b32 s6, s4, 1
	s_mul_i32 s5, s5, 0x482000
	s_mul_i32 s6, s6, 0x9040
	s_add_i32 s5, s5, s6
	s_add_i32 s5, s5, 0x2000
	s_add_u32 s8, s44, s5
	s_addc_u32 s9, s45, 0
	s_add_u32 s10, s8, 0x4820
	s_addc_u32 s11, s9, 0
	v_mul_u32_u24_e32 v168, 0x12080, v230
	v_lshlrev_b32_e32 v128, 2, v230
	v_or_b32_e32 v130, 0x100, v128
	s_mov_b64 s[16:17], 0x2000
	global_load_dwordx4 v[152:155], v168, s[8:9]
	global_load_dwordx4 v[156:159], v168, s[8:9] offset:16
	global_load_dwordx4 v[160:163], v168, s[10:11]
	global_load_dwordx4 v[164:167], v168, s[10:11] offset:16
	v_lshlrev_b32_e32 v170, 4, v230
	s_lshl_b32 s6, s4, 12
	v_add_u32_e32 v169, s6, v170
	v_add_u32_e32 v170, 0x8800, v170
	s_waitcnt vmcnt(3)
	ds_write_b128 v169, v[152:155] offset:34816
	s_waitcnt vmcnt(2)
	ds_write_b128 v169, v[156:159] offset:35840
	s_waitcnt vmcnt(1)
	ds_write_b128 v169, v[160:163] offset:36864
	s_waitcnt vmcnt(0)
	ds_write_b128 v169, v[164:167] offset:37888
	s_waitcnt lgkmcnt(0)
	s_barrier
	ds_read_b128 v[0:3], v170
	ds_read_b128 v[4:7], v170 offset:1024
	ds_read_b128 v[8:11], v170 offset:2048
	ds_read_b128 v[12:15], v170 offset:3072
	ds_read_b128 v[16:19], v170 offset:4096
	ds_read_b128 v[20:23], v170 offset:5120
	ds_read_b128 v[24:27], v170 offset:6144
	ds_read_b128 v[28:31], v170 offset:7168
	ds_read_b128 v[32:35], v170 offset:8192
	ds_read_b128 v[36:39], v170 offset:9216
	ds_read_b128 v[40:43], v170 offset:10240
	ds_read_b128 v[44:47], v170 offset:11264
	ds_read_b128 v[48:51], v170 offset:12288
	ds_read_b128 v[52:55], v170 offset:13312
	ds_read_b128 v[56:59], v170 offset:14336
	ds_read_b128 v[60:63], v170 offset:15360
	ds_read_b128 v[64:67], v170 offset:16384
	ds_read_b128 v[68:71], v170 offset:17408
	ds_read_b128 v[72:75], v170 offset:18432
	ds_read_b128 v[76:79], v170 offset:19456
	ds_read_b128 v[80:83], v170 offset:20480
	ds_read_b128 v[84:87], v170 offset:21504
	ds_read_b128 v[88:91], v170 offset:22528
	ds_read_b128 v[92:95], v170 offset:23552
	ds_read_b128 v[96:99], v170 offset:24576
	ds_read_b128 v[100:103], v170 offset:25600
	ds_read_b128 v[104:107], v170 offset:26624
	ds_read_b128 v[108:111], v170 offset:27648
	ds_read_b128 v[112:115], v170 offset:28672
	ds_read_b128 v[116:119], v170 offset:29696
	ds_read_b128 v[120:123], v170 offset:30720
	ds_read_b128 v[124:127], v170 offset:31744
	s_waitcnt lgkmcnt(0)
	v_readlane_b32 s37, v254, 5
	v_readlane_b32 s46, v254, 14
	v_readlane_b32 s47, v254, 15
	v_mov_b32_e32 v129, v179
	v_lshlrev_b32_e32 v178, 4, v230
	v_readlane_b32 s38, v254, 6
	v_readlane_b32 s39, v254, 7
	v_readlane_b32 s40, v254, 8
	v_or_b32_e32 v132, 0x200, v128
	v_or_b32_e32 v134, 0x300, v128
	v_subrev_co_u32_e64 v231, s[0:1], 4, v230
	v_lshl_add_u64 v[180:181], s[36:37], 0, v[178:179]
	v_lshl_add_u64 v[136:137], s[46:47], 0, v[128:129]
	v_lshlrev_b32_e32 v178, 3, v230
	v_cmp_gt_u32_e32 vcc, 8, v230
	s_xor_b64 s[24:25], s[0:1], -1
	s_lshl_b32 s3, s33, 5
	v_cmp_eq_u32_e64 s[0:1], 1, v230
	v_cmp_eq_u32_e64 s[14:15], 2, v230
	v_cmp_eq_u32_e64 s[4:5], 3, v230
	v_cmp_eq_u32_e64 s[6:7], 4, v230
	v_cmp_eq_u32_e64 s[8:9], 5, v230
	v_cmp_eq_u32_e64 s[10:11], 6, v230
	v_cmp_eq_u32_e64 s[12:13], 7, v230
	v_lshl_add_u64 v[182:183], v[136:137], 0, s[16:17]
	v_lshl_add_u64 v[184:185], s[94:95], 0, v[178:179]
	s_mov_b64 s[26:27], 0
	v_lshlrev_b32_e32 v178, 2, v128
	v_lshlrev_b32_e32 v186, 2, v130
	v_lshlrev_b32_e32 v188, 2, v132
	v_lshlrev_b32_e32 v190, 2, v134
	v_mov_b32_e32 v232, 0x3727c5ac
	s_mov_b32 s36, 0x800000
	s_mov_b32 s37, 0x3f2aaaab
	v_mov_b32_e32 v233, 0x3ecc95a3
	s_mov_b32 s38, 0x3f317218
	s_mov_b32 s39, 0x7f800000
	s_mov_b32 s40, 0x33800000
	v_mov_b32_e32 v234, 0x7f800000
	v_mov_b32_e32 v235, 0x7fc00000
	v_mov_b32_e32 v236, 0xff800000
	v_mov_b32_e32 v192, 0x3f317218
	v_readlane_b32 s41, v254, 9
	v_readlane_b32 s42, v254, 10
	v_readlane_b32 s43, v254, 11
	v_readlane_b32 s48, v254, 16
	v_readlane_b32 s49, v254, 17
	v_readlane_b32 s50, v254, 18
	v_readlane_b32 s51, v254, 19
	global_load_dword v251, v[182:183], off
	s_mov_b64 s[76:77], 0x1000
	s_mov_b64 s[78:79], 0x2000
	s_branch .LBB0_189

; DI int fresh_tid() { int t = threadIdx.x; asm volatile("" : "+v"(t)); return t; }
; DI unsigned xb_ld(unsigned* p)              { return __hip_atomic_load(p, __ATOMIC_RELAXED, __HIP_MEMORY_SCOPE_AGENT); }
; DI unsigned xb_xcc_id() { return (unsigned)__builtin_amdgcn_s_getreg((3 << 11) | 20) & 0xFu; }
; DI void xcd_barrier_complete(unsigned* bar, unsigned x, unsigned& nloc, unsigned& nx) {
;     ...
;     for (;;) {
;         sum = 0u; cnt = 0u; mine = 0u;
; #pragma unroll
;         for (unsigned j = 0; j < 16; ++j) { const unsigned c = xb_ld(&bar[XB_XCNT(j)]); sum += c; cnt += (c > 0u) ? 1u : 0u; mine = (j == x) ? c : mine; }
; DI void xcd_barrier(unsigned* bar, volatile __attribute__((address_space(3))) unsigned* st) {
;     asm volatile("s_waitcnt vmcnt(0)" ::: "memory");
;     __syncthreads();
;     if (fresh_tid() == 0) {
;         __builtin_amdgcn_s_waitcnt(0);
;         const unsigned x = xb_xcc_id();
;         unsigned nloc = st[0], nx = st[1];
;         if (nloc == 0u) { xcd_barrier_complete(bar, x, nloc, nx); st[0] = nloc; st[1] = nx; }
.LBB0_222:
	s_or_b64 exec, exec, s[0:1]
	s_waitcnt vmcnt(0)
	v_mov_b32_e32 v0, v250
	s_barrier
	s_getpc_b64 vcc
	v_mov_b32_e32 v2, vcc_lo
	v_mov_b32_e32 v3, vcc_hi
	v_lshlrev_b32_e32 v1, 6, v0
	v_cmp_lt_u32_e32 vcc, 63, v0
	s_and_saveexec_b64 s[0:1], vcc
	s_cbranch_execz .Lcpf_s2
	v_add_co_u32_e32 v2, vcc, v2, v1
	s_nop 1
	v_addc_co_u32_e32 v3, vcc, 0, v3, vcc
	global_load_dword v4, v[2:3], off
.Lcpf_s2:
	s_or_b64 exec, exec, s[0:1]
	s_nop 0
	v_cmp_eq_u32_e32 vcc, 0, v0
	s_and_saveexec_b64 s[0:1], vcc
	s_cbranch_execz .LBB0_274
	v_mov_b32_e32 v0, 0
	s_waitcnt vmcnt(0) expcnt(0) lgkmcnt(0)
	s_getreg_b32 s3, hwreg(HW_REG_XCC_ID, 0, 4)
	ds_read_b32 v2, v0
	ds_read_b32 v1, v0 offset:4
	s_and_b32 s3, s3, 15
	s_waitcnt lgkmcnt(1)
	v_cmp_ne_u32_e32 vcc, 0, v2
	s_cbranch_vccnz .LBB0_238
	s_add_u32 s6, s70, 0x34e2300
	s_addc_u32 s7, s71, 0
	s_add_u32 s8, s70, 0x34e2500
	s_addc_u32 s9, s71, 0
	s_add_u32 s10, s70, 0x34e2600
	s_addc_u32 s11, s71, 0
	s_add_u32 s12, s70, 0x34e2700
	s_addc_u32 s13, s71, 0
	s_add_u32 s14, s70, 0x34e2800
	s_addc_u32 s15, s71, 0
	s_add_u32 s16, s70, 0x34e2900
	s_addc_u32 s17, s71, 0
	s_add_u32 s22, s70, 0x34e2a00
	s_addc_u32 s23, s71, 0
	s_add_u32 s24, s70, 0x34e2b00
	s_addc_u32 s25, s71, 0
	s_add_u32 s26, s70, 0x34e2c00
	s_addc_u32 s27, s71, 0
	s_add_u32 s28, s70, 0x34e2d00
	s_addc_u32 s29, s71, 0
	s_add_u32 s30, s70, 0x34e2e00
	s_addc_u32 s31, s71, 0
	s_add_u32 s34, s70, 0x34e2f00
	s_addc_u32 s35, s71, 0
	s_add_u32 s36, s70, 0x34e3000
	s_addc_u32 s37, s71, 0
	s_add_u32 s38, s70, 0x34e3100
	s_addc_u32 s39, s71, 0
	s_add_u32 s40, s70, 0x34e3200
	s_addc_u32 s41, s71, 0
	s_add_u32 s42, s70, 0x34e3300
	s_addc_u32 s43, s71, 0
	s_add_u32 s44, s70, 0x34e3400
	s_addc_u32 s45, s71, 0
	s_mov_b32 s52, 1
	s_branch .LBB0_226

; #define PG8_LAS __attribute__((address_space(3)))
; #define PG8_BAR __builtin_amdgcn_s_barrier()
;     DI bool next(int i, Unit& u) const {
;         const long L = (long)i * G + c; if (L >= nwg) return false;
;         int wgid = (int)L; { const int q = nwg / NXCD, r = nwg % NXCD, xcd = wgid % NXCD, off = wgid / NXCD; wgid = (xcd < r ? xcd * (q + 1) : r * (q + 1) + (xcd - r) * q) + off; }
;         const int nig = WGM * nN, gid = wgid / nig, fm = gid * WGM, gsz = (nM - fm) < WGM ? (nM - fm) : WGM;
;         u.pm = fm + ((wgid % nig) % gsz); u.pn = (wgid % nig) / gsz; return true;
;     }
; template <class Epi>
; DI void gemm_phase(PG8_LAS unsigned char* lds, const Gemm g, const StaticOrder& S, const Epi& E) {
;     int tid = threadIdx.x; asm volatile("" : "+v"(tid));
;     const int wid = __builtin_amdgcn_readfirstlane(tid >> 6), lane = tid & 63, wr = wid >> 2, wc = wid & 3, fr = lane & 15, fq = lane >> 4;
;     const int nt = g.K / BK;
;     unsigned voffA[2], voffB[2];
; #pragma unroll
;     for (int i = 0; i < 2; ++i) { int R, C; stage_rc(tid * 16 + i * 8192, R, C); const int Rb = (R & ~31) + perm32(R & 31);
;         voffA[i] = (unsigned)(R * g.lda + C) * 2u; voffB[i] = (unsigned)(Rb * g.ldb + C) * 2u; }
;     const size_t kstep = (size_t)(BK * 2);
;     const size_t hstepA = (size_t)HALF * g.lda * 2, hstepB = (size_t)HALF * g.ldb * 2;
;     const size_t tstepA = 2 * hstepA, tstepB = 2 * hstepB;
;     const unsigned ldsw = (unsigned)wid * 1024u;
;     const int aoff = lds_byte(wr * 64 + fr, fq * 8), boff = lds_byte(wc * 32 + fr, fq * 8);
;     ...
;     Unit cur, nxt; int ui = 0;
;     if (!S.next(0, cur)) return;
;     f32x4 acc[2][2][4][2];
; #pragma unroll
;     for (int a = 0; a < 2; ++a)
; #pragma unroll
;         for (int b = 0; b < 2; ++b)
; #pragma unroll
;             for (int m = 0; m < 4; ++m)
; #pragma unroll
;                 for (int n = 0; n < 2; ++n) acc[a][b][m][n] = (f32x4){0.f, 0.f, 0.f, 0.f};
;     bf16x8 At[4][2], B0[2][2], B1[2][2];
;     const char* cA = (const char*)g.A + (size_t)cur.pm * tstepA + (size_t)cur.pn * g.a_pn_off; const char* cB = (const char*)g.Bt + (size_t)cur.pn * tstepB;
;     PG8_STAGE(PG8_SB(0, 0), cB, voffB); PG8_STAGE(PG8_SB(0, 1), cB + hstepB, voffB); PG8_STAGE(PG8_SA(0, 0), cA, voffA); PG8_STAGE(PG8_SA(0, 1), cA + hstepA, voffA);
;     if (wr == 1) PG8_BAR;
;     PG8_WAIT_V(2); PG8_BAR;
.LBB0_274:
	v_writelane_b32 v254, s62, 54
	s_nop 1
	v_writelane_b32 v254, s63, 55
	s_or_b64 exec, exec, s[0:1]
	s_add_u32 s0, s70, 0x8000000
	s_addc_u32 s1, s71, 0
	s_add_u32 s92, s70, 0xc000000
	s_addc_u32 s93, s71, 0
	s_add_u32 s72, s70, 0x10000000
	v_writelane_b32 v254, s0, 56
	s_addc_u32 s73, s71, 0
	s_add_u32 s62, s70, 0x1c000000
	v_writelane_b32 v254, s1, 57
	s_addc_u32 s63, s71, 0
	v_mov_b32_e32 v11, v250
	v_writelane_b32 v254, s72, 58
	s_waitcnt lgkmcnt(0)
	s_waitcnt vmcnt(0)
	s_barrier
	s_cmpk_gt_i32 s2, 0x8ff
	v_readfirstlane_b32 s1, v11
	v_writelane_b32 v254, s73, 59
	s_cbranch_scc1 .LBB0_305
	v_lshlrev_b32_e32 v0, 4, v11
	v_add_u32_e32 v1, 0x2000, v0
	v_ashrrev_i32_e32 v2, 31, v1
	v_lshrrev_b32_e32 v2, 22, v2
	v_add_u32_e32 v2, v1, v2
	v_ashrrev_i32_e32 v8, 10, v2
	v_mul_i32_i24_e32 v2, 0x400, v8
	v_sub_u32_e32 v1, v1, v2
	v_lshrrev_b32_e32 v2, 4, v1
	v_bitop3_b32 v1, v2, v1, 32 bitop3:0x6c
	v_ashrrev_i32_e32 v2, 31, v1
	v_lshrrev_b32_e32 v2, 26, v2
	v_add_u32_e32 v2, v1, v2
	v_lshlrev_b32_e32 v3, 3, v8
	v_ashrrev_i32_e32 v9, 6, v2
	v_and_b32_e32 v3, -16, v3
	v_add_u32_e32 v3, v9, v3
	v_and_b32_e32 v4, 3, v9
	s_mov_b32 s0, 0x1fffe0
	v_lshrrev_b32_e32 v5, 2, v3
	v_lshlrev_b32_e32 v6, 1, v3
	v_and_b32_e32 v2, 0xc0, v2
	v_and_or_b32 v4, v3, s0, v4
	v_and_b32_e32 v5, 4, v5
	v_and_b32_e32 v6, 24, v6
	v_sub_u32_e32 v1, v1, v2
	v_mov_b32_e32 v2, 1
	v_or3_b32 v4, v4, v5, v6
	v_lshlrev_b32_e32 v5, 5, v8
	v_ashrrev_i16_sdwa v1, v2, sext(v1) dst_sel:DWORD dst_unused:UNUSED_PAD src0_sel:DWORD src1_sel:BYTE_0
	v_and_b32_e32 v5, 32, v5
	v_bfe_i32 v10, v1, 0, 16
	v_add_lshl_u32 v1, v5, v10, 1
	v_lshl_add_u32 v144, v4, 11, v1
	v_lshl_add_u32 v146, v3, 11, v1
	v_bfe_i32 v1, v11, 27, 1
	v_lshrrev_b32_e32 v1, 22, v1
	v_add_u32_e32 v1, v0, v1
	v_and_b32_e32 v1, 0xfffffc00, v1
	v_sub_u32_e32 v0, v0, v1
	v_lshrrev_b32_e32 v1, 4, v0
	v_ashrrev_i32_e32 v3, 31, v11
	v_bitop3_b32 v0, v1, v0, 32 bitop3:0x6c
	v_lshrrev_b32_e32 v3, 26, v3
	v_ashrrev_i32_e32 v1, 31, v0
	v_add_u32_e32 v3, v11, v3
	v_lshrrev_b32_e32 v1, 26, v1
	v_ashrrev_i32_e32 v13, 6, v3
	v_add_u32_e32 v1, v0, v1
	v_lshlrev_b32_e32 v3, 3, v13
	v_ashrrev_i32_e32 v12, 6, v1
	v_and_b32_e32 v3, -16, v3
	v_add_u32_e32 v3, v12, v3
	v_and_b32_e32 v4, 3, v12
	s_ashr_i32 s3, s2, 31
	v_and_or_b32 v4, v3, s0, v4
	s_lshr_b32 s0, s3, 29
	s_add_i32 s0, s2, s0
	s_ashr_i32 s6, s1, 6
	s_ashr_i32 s7, s0, 3
	s_and_b32 s0, s0, -8
	s_ashr_i32 s10, s1, 8
	s_lshl_b32 s36, s6, 10
	s_sub_i32 s0, s2, s0
	s_cmp_lt_i32 s0, 0
	s_movk_i32 s37, 0x121
	s_cselect_b32 s8, s37, 0x120
	s_mul_i32 s0, s0, s8
	s_add_i32 s0, s0, s7
	s_mul_hi_i32 s7, s0, 0x38e38e39
	s_lshr_b32 s8, s7, 31
	s_ashr_i32 s7, s7, 4
	s_add_i32 s7, s7, s8
	s_lshl_b32 s8, s7, 2
	s_mulk_i32 s7, 0x48
	s_sub_i32 s7, s0, s7
	s_bfe_i32 s0, s7, 0x80000
	s_bfe_u32 s0, s0, 0x2000d
	s_add_i32 s9, s7, s0
	s_bfe_i32 s0, s9, 0x80000
	s_and_b32 s9, s9, 0xfc
	s_sub_i32 s7, s7, s9
	s_sext_i32_i16 s0, s0
	s_sext_i32_i8 s7, s7
	v_lshrrev_b32_e32 v5, 2, v3
	v_lshlrev_b32_e32 v6, 1, v3
	v_and_b32_e32 v1, 0xc0, v1
	s_lshr_b32 s0, s0, 2
	s_add_i32 s26, s8, s7
	v_and_b32_e32 v5, 4, v5
	v_and_b32_e32 v6, 24, v6
	v_sub_u32_e32 v0, v0, v1
	s_ashr_i32 s27, s26, 31
	s_bfe_i64 s[12:13], s[0:1], 0x100000
	v_or3_b32 v4, v4, v5, v6
	v_lshlrev_b32_e32 v5, 5, v13
	v_ashrrev_i16_sdwa v0, v2, sext(v0) dst_sel:DWORD dst_unused:UNUSED_PAD src0_sel:DWORD src1_sel:BYTE_0
	s_lshl_b64 s[8:9], s[26:27], 19
	s_lshl_b64 s[12:13], s[12:13], 19
	v_and_b32_e32 v5, 32, v5
	v_bfe_i32 v14, v0, 0, 16
	s_add_u32 s30, s70, s12
	v_add_lshl_u32 v0, v5, v14, 1
	s_addc_u32 s31, s71, s13
	s_add_i32 s38, s36, 16
	v_lshl_add_u32 v148, v4, 11, v0
	s_add_i32 m0, s38, 0x10000
	v_lshl_add_u32 v150, v3, 11, v0
	global_load_lds_dwordx4 v148, s[30:31]
	s_add_i32 m0, s38, 0x12000
	s_add_u32 s12, s30, 0x40000
	global_load_lds_dwordx4 v144, s[30:31]
	s_addc_u32 s13, s31, 0
	s_add_i32 m0, s38, 0x14000
	v_mov_b32_e32 v153, 0
	global_load_lds_dwordx4 v148, s[12:13]
	s_add_i32 m0, s38, 0x16000
	s_add_u32 s28, s94, s8
	s_addc_u32 s29, s95, s9
	s_add_i32 s39, s38, 0x2000
	global_load_lds_dwordx4 v144, s[12:13]
	s_mov_b32 m0, s38
	s_add_u32 s8, s28, 0x40000
	global_load_lds_dwordx4 v150, s[28:29]
	s_mov_b32 m0, s39
	s_addc_u32 s9, s29, 0
	s_add_i32 s40, s38, 0x4000
	global_load_lds_dwordx4 v146, s[28:29]
	s_mov_b32 m0, s40
	s_add_i32 s41, s38, 0x6000
	global_load_lds_dwordx4 v150, s[8:9]
	s_mov_b32 m0, s41
	v_mov_b32_e32 v149, v153
	global_load_lds_dwordx4 v146, s[8:9]
	v_mov_b32_e32 v145, v153
	v_mov_b32_e32 v151, v153
	v_mov_b32_e32 v147, v153
	s_cmp_eq_u32 s10, 1
	s_mov_b32 s7, 0
	v_lshl_add_u64 v[6:7], s[30:31], 0, v[148:149]
	v_lshl_add_u64 v[4:5], s[30:31], 0, v[144:145]
	v_lshl_add_u64 v[2:3], s[28:29], 0, v[150:151]
	s_cselect_b64 s[8:9], -1, 0
	s_cmp_lg_u32 s10, 1
	v_lshl_add_u64 v[0:1], s[28:29], 0, v[146:147]
	s_cbranch_scc1 .LBB0_277
	s_barrier

; DI int fresh_tid() { int t = threadIdx.x; asm volatile("" : "+v"(t)); return t; }
; DI void xcd_barrier(unsigned* bar, volatile __attribute__((address_space(3))) unsigned* st) {
;     asm volatile("s_waitcnt vmcnt(0)" ::: "memory");
;     __syncthreads();
;     if (fresh_tid() == 0) {
.LBB0_305:
	s_waitcnt vmcnt(0)
	v_mov_b32_e32 v0, v250
	s_waitcnt lgkmcnt(0)
	s_barrier
	s_getpc_b64 vcc
	v_mov_b32_e32 v2, vcc_lo
	v_mov_b32_e32 v3, vcc_hi
	v_lshlrev_b32_e32 v1, 6, v0
	v_cmp_lt_u32_e32 vcc, 63, v0
	s_and_saveexec_b64 s[0:1], vcc
	s_cbranch_execz .Lcpf_s3
	v_add_co_u32_e32 v2, vcc, v2, v1
	s_nop 1
	v_addc_co_u32_e32 v3, vcc, 0, v3, vcc
	global_load_dword v4, v[2:3], off

; template <class LA, class LB>
; DI void gemm_tile(unsigned char* smem, const int tid, int nk, LA la, LB lb, f32x4 (&acc)[4][4]) {
;     const int lane = tid & 63, wid = tid >> 6;
;     const int wf = wid >> 1, wt = wid & 1;
;     const int lr = tid >> 3, lc = tid & 7;
;     unsigned char* sA = smem;
;     unsigned char* sB = smem + 32768;
; #pragma unroll
;     for (int i = 0; i < 4; ++i)
; #pragma unroll
;         for (int j = 0; j < 4; ++j) acc[i][j] = f32x4{0.f, 0.f, 0.f, 0.f};
;     uint4 ra[4], rb[4], na[4], nb[4];
; #pragma unroll
;     for (int i = 0; i < 4; ++i) { ra[i] = la(lr + 32 * i, lc * 8); rb[i] = lb(lr + 32 * i, lc * 8); }
;     if (nk > 1) {
; #pragma unroll
;         for (int i = 0; i < 4; ++i) { na[i] = la(lr + 32 * i, 64 + lc * 8); nb[i] = lb(lr + 32 * i, 64 + lc * 8); }
;     }
;     const int woff = lr * 128 + ((lc ^ ((lr >> 1) & 7)) << 4);
; #pragma unroll
;     for (int i = 0; i < 4; ++i) { *(uint4*)(sA + woff + i * 4096) = ra[i]; *(uint4*)(sB + woff + i * 4096) = rb[i]; }
; DI void phase3(const Params& p, unsigned char* smem, const int tid, const int vb, const int nvb) {
;     ...
;     for (int it = vb; it < 256; it += nvb) {
;         const int g = it >> 3, nt = (it >> 1) & 3, kh = it & 1;
;         f32x4 acc[4][4];
;         auto lb = [=](int r, int k) -> uint4 { return *(const uint4*)(us + ((size_t)g * 512 + nt * 128 + r) * 1024 + kh * 512 + k); };
;         gemm_tile(smem, tid, 8, RowMajor{emat + (size_t)g * 128 * 1024 + kh * 512, 1024}, lb, acc);
.LBB0_357:
	s_or_b64 exec, exec, s[0:1]
	v_mov_b32_e32 v160, v250
	s_waitcnt lgkmcnt(0)
	s_waitcnt vmcnt(0)
	s_barrier
	s_add_u32 s14, s68, 0x3000000
	v_ashrrev_i32_e32 v0, 8, v160
	v_add_u32_e32 v162, s54, v0
	s_movk_i32 s0, 0x100
	s_movk_i32 s3, 0xff
	v_and_b32_e32 v161, 0xff, v160
	s_addc_u32 s15, s69, 0
	v_cmp_gt_i32_e32 vcc, s0, v162
	v_lshrrev_b32_e32 v45, 2, v160
	v_lshlrev_b32_e32 v44, 6, v0
	s_and_saveexec_b64 s[0:1], vcc
	s_cbranch_execz .LBB0_360
	v_lshrrev_b32_e32 v11, 1, v161
	v_and_b32_e32 v18, 64, v11
	v_lshl_add_u32 v2, v0, 16, 16
	v_lshrrev_b32_e32 v0, 3, v161
	v_lshlrev_b32_e32 v20, 4, v161
	v_and_or_b32 v19, v160, 15, v18
	v_lshlrev_b32_e32 v1, 7, v0
	v_xor_b32_e32 v7, v20, v160
	s_movk_i32 s6, 0x70
	v_lshl_add_u32 v25, v19, 7, v2
	v_lshlrev_b32_e32 v19, 7, v161
	v_and_or_b32 v1, v7, s6, v1
	v_bfe_u32 v7, v160, 4, 2
	v_and_b32_e32 v19, 0x2780, v19
	v_add_u32_e32 v1, v2, v1
	v_bfe_u32 v15, v161, 1, 3
	v_add_u32_e32 v26, v2, v19
	v_bitop3_b32 v2, v11, v7, 7 bitop3:0x6c
	v_lshlrev_b32_e32 v27, 4, v2
	v_bitop3_b32 v2, v7, v15, 4 bitop3:0x36
	v_bfe_u32 v21, v160, 8, 1
	v_mov_b32_e32 v3, 0
	v_lshlrev_b32_e32 v28, 4, v2
	v_lshlrev_b32_e32 v2, 10, v21
	v_and_or_b32 v24, v45, 12, v18
	v_lshl_add_u64 v[22:23], s[70:71], 0, v[2:3]
	v_lshl_add_u64 v[18:19], s[62:63], 0, v[2:3]
	v_and_b32_e32 v2, 0x70, v20
	v_or_b32_e32 v6, 32, v0
	v_or_b32_e32 v10, 64, v0
	v_or_b32_e32 v14, 0x60, v0
	v_and_b32_e32 v7, 0x4f, v160
	v_lshlrev_b32_e32 v20, 23, v21
	v_mov_b32_e32 v21, v3
	v_lshl_add_u64 v[22:23], v[22:23], 0, v[2:3]
	s_mov_b64 s[6:7], 0x225c000
	v_lshlrev_b32_e32 v4, 11, v0
	v_mov_b32_e32 v5, v3
	v_lshlrev_b32_e32 v8, 11, v6
	v_mov_b32_e32 v9, v3
	v_lshlrev_b32_e32 v12, 11, v10
	v_mov_b32_e32 v13, v3
	v_lshlrev_b32_e32 v16, 11, v14
	v_mov_b32_e32 v17, v3
	v_or_b32_e32 v11, 16, v7
	v_or_b32_e32 v15, 32, v7
	v_or_b32_e32 v46, 48, v7
	v_lshl_add_u64 v[18:19], v[18:19], 0, v[2:3]
	v_lshl_add_u64 v[20:21], s[14:15], 0, v[20:21]
	v_lshl_add_u64 v[22:23], v[22:23], 0, s[6:7]
	v_lshl_add_u32 v47, s2, 7, v44
	s_lshl_b32 s8, s33, 7
	s_mov_b64 s[6:7], 0
	v_lshlrev_b32_e32 v24, 2, v24
	v_add_u32_e32 v48, v25, v27
	v_add_u32_e32 v49, v26, v27
	v_add_u32_e32 v50, v25, v28
	v_add_u32_e32 v51, v26, v28
	v_mov_b32_e32 v25, v3
	v_mov_b32_e32 v52, v162

; DI int fresh_tid() { int t = threadIdx.x; asm volatile("" : "+v"(t)); return t; }
; DI unsigned xb_ld(unsigned* p)              { return __hip_atomic_load(p, __ATOMIC_RELAXED, __HIP_MEMORY_SCOPE_AGENT); }
; DI unsigned xb_xcc_id() { return (unsigned)__builtin_amdgcn_s_getreg((3 << 11) | 20) & 0xFu; }
; DI void xcd_barrier_complete(unsigned* bar, unsigned x, unsigned& nloc, unsigned& nx) {
;     ...
;     for (;;) {
;         sum = 0u; cnt = 0u; mine = 0u;
; #pragma unroll
;         for (unsigned j = 0; j < 16; ++j) { const unsigned c = xb_ld(&bar[XB_XCNT(j)]); sum += c; cnt += (c > 0u) ? 1u : 0u; mine = (j == x) ? c : mine; }
; DI void xcd_barrier(unsigned* bar, volatile __attribute__((address_space(3))) unsigned* st) {
;     asm volatile("s_waitcnt vmcnt(0)" ::: "memory");
;     __syncthreads();
;     if (fresh_tid() == 0) {
;         __builtin_amdgcn_s_waitcnt(0);
;         const unsigned x = xb_xcc_id();
;         unsigned nloc = st[0], nx = st[1];
;         if (nloc == 0u) { xcd_barrier_complete(bar, x, nloc, nx); st[0] = nloc; st[1] = nx; }
.LBB0_382:
	s_or_b64 exec, exec, s[16:17]
	s_waitcnt vmcnt(0)
	v_mov_b32_e32 v0, v250
	s_waitcnt lgkmcnt(0)
	s_barrier
	s_getpc_b64 vcc
	v_mov_b32_e32 v2, vcc_lo
	v_mov_b32_e32 v3, vcc_hi
	v_lshlrev_b32_e32 v1, 6, v0
	v_cmp_lt_u32_e32 vcc, 63, v0
	s_and_saveexec_b64 s[0:1], vcc
	s_cbranch_execz .Lcpf_s4
	v_add_co_u32_e32 v2, vcc, v2, v1
	s_nop 1
	v_addc_co_u32_e32 v3, vcc, 0, v3, vcc
	global_load_dword v4, v[2:3], off
.Lcpf_s4:
	s_or_b64 exec, exec, s[0:1]
	s_nop 0
	v_cmp_eq_u32_e32 vcc, 0, v0
	s_and_saveexec_b64 s[0:1], vcc
	s_cbranch_execz .LBB0_434
	v_mov_b32_e32 v0, 0
	s_waitcnt vmcnt(0) expcnt(0) lgkmcnt(0)
	s_getreg_b32 s3, hwreg(HW_REG_XCC_ID, 0, 4)
	ds_read_b32 v2, v0
	ds_read_b32 v1, v0 offset:4
	s_and_b32 s3, s3, 15
	s_waitcnt lgkmcnt(1)
	v_cmp_ne_u32_e32 vcc, 0, v2
	s_cbranch_vccnz .LBB0_398
	s_add_u32 s4, s70, 0x34e2300
	s_addc_u32 s5, s71, 0
	s_add_u32 s6, s70, 0x34e2500
	s_addc_u32 s7, s71, 0
	s_add_u32 s8, s70, 0x34e2600
	s_addc_u32 s9, s71, 0
	s_add_u32 s10, s70, 0x34e2700
	s_addc_u32 s11, s71, 0
	s_add_u32 s12, s70, 0x34e2800
	s_addc_u32 s13, s71, 0
	s_add_u32 s16, s70, 0x34e2900
	s_addc_u32 s17, s71, 0
	s_add_u32 s20, s70, 0x34e2a00
	s_addc_u32 s21, s71, 0
	s_add_u32 s22, s70, 0x34e2b00
	s_addc_u32 s23, s71, 0
	s_add_u32 s24, s70, 0x34e2c00
	s_addc_u32 s25, s71, 0
	s_add_u32 s26, s70, 0x34e2d00
	s_addc_u32 s27, s71, 0
	s_add_u32 s28, s70, 0x34e2e00
	s_addc_u32 s29, s71, 0
	s_add_u32 s30, s70, 0x34e2f00
	s_addc_u32 s31, s71, 0
	s_add_u32 s34, s70, 0x34e3000
	s_addc_u32 s35, s71, 0
	s_add_u32 s36, s70, 0x34e3100
	s_addc_u32 s37, s71, 0
	s_add_u32 s38, s70, 0x34e3200
	s_addc_u32 s39, s71, 0
	s_add_u32 s40, s70, 0x34e3300
	s_addc_u32 s41, s71, 0
	s_add_u32 s42, s70, 0x34e3400
	s_addc_u32 s43, s71, 0
	s_mov_b32 s50, 1
	s_branch .LBB0_386

; DI void phase4_small(const Params& p, unsigned char* smem) {
;     ...
;     if (blockIdx.x >= gridDim.x - 2) {
;         const int bh = (blockIdx.x - (gridDim.x - 2)) * 8 + wid;
;         const float* aa = (const float*)(ws + OFF_AARR) + bh * 128;
;         const float* bl = (const float*)(ws + OFF_BLAST) + bh * 128;
;         float* ms = (float*)(ws + OFF_MST) + bh * 132;
;         const float p0 = bl[2 * lane], q0 = aa[2 * lane], p1 = bl[2 * lane + 1], q1 = aa[2 * lane + 1];
;         float P = p0 + p1, Q = fmaxf(q0 + p1, q1);
; #pragma unroll
;         for (int d = 1; d < 64; d <<= 1) {
;             const float Pp = __shfl_up(P, d, 64), Qp = __shfl_up(Q, d, 64);
;             if (lane >= d) { Q = fmaxf(Qp + P, Q); P = Pp + P; }
;         }
;         float Pe = __shfl_up(P, 1, 64), Qe = __shfl_up(Q, 1, 64);
;         const float m_even = (lane == 0) ? 0.f : fmaxf(Pe, Qe);
;         const float m_odd = fmaxf(m_even + p0, q0);
;         ms[2 * lane] = m_even; ms[2 * lane + 1] = m_odd;
;         if (lane == 63) ms[128] = fmaxf(P, Q);
;     }
.LBB0_434:
	s_or_b64 exec, exec, s[0:1]
	v_mov_b32_e32 v101, v250
	s_waitcnt lgkmcnt(0)
	s_waitcnt vmcnt(0)
	s_barrier
	s_add_i32 s0, s33, -2
	v_and_b32_e32 v100, 63, v101
	v_ashrrev_i32_e32 v102, 6, v101
	s_cmp_lt_u32 s2, s0
	v_lshlrev_b32_e32 v0, 3, v100
	s_cbranch_scc1 .LBB0_438
	s_sub_i32 s0, s2, s33
	s_lshl_b32 s0, s0, 3
	v_add3_u32 v10, s0, 16, v102
	v_lshlrev_b32_e32 v2, 7, v10
	v_ashrrev_i32_e32 v3, 31, v2
	v_lshl_add_u64 v[2:3], v[2:3], 2, s[70:71]
	v_mov_b32_e32 v1, 0
	v_lshl_add_u64 v[2:3], v[2:3], 0, v[0:1]
	v_add_co_u32_e32 v4, vcc, 0x33de000, v2
	s_movk_i32 s3, 0x84
	s_nop 0
	v_addc_co_u32_e32 v5, vcc, 0, v3, vcc
	v_add_co_u32_e32 v2, vcc, 0x33dc000, v2
	s_mov_b64 s[4:5], 0x33e0000
	s_nop 0
	v_addc_co_u32_e32 v3, vcc, 0, v3, vcc
	global_load_dwordx2 v[6:7], v[4:5], off
	global_load_dwordx2 v[8:9], v[2:3], off
	v_mbcnt_lo_u32_b32 v2, -1, 0
	v_mbcnt_hi_u32_b32 v2, -1, v2
	v_and_b32_e32 v3, 64, v2
	v_add_u32_e32 v4, -1, v2
	v_cmp_lt_i32_e32 vcc, v4, v3
	v_add_u32_e32 v5, -2, v2
	v_add_u32_e32 v11, -4, v2
	v_cndmask_b32_e32 v4, v4, v2, vcc
	v_lshlrev_b32_e32 v15, 2, v4
	v_cmp_lt_i32_e32 vcc, v5, v3
	v_cmp_lt_i32_e64 s[0:1], v11, v3
	v_add_u32_e32 v12, -8, v2
	v_cndmask_b32_e32 v5, v5, v2, vcc
	v_cmp_eq_u32_e32 vcc, 0, v100
	v_lshlrev_b32_e32 v5, 2, v5
	v_cndmask_b32_e64 v11, v11, v2, s[0:1]
	v_cmp_gt_u32_e64 s[0:1], 2, v100
	v_lshlrev_b32_e32 v11, 2, v11
	v_add_u32_e32 v13, -16, v2
	v_subrev_u32_e32 v14, 32, v2
	s_waitcnt vmcnt(0)
	v_add_f32_e32 v4, v6, v7
	v_add_f32_e32 v7, v8, v7
	v_max_f32_e32 v9, v9, v9
	v_max_f32_e32 v7, v7, v9
	ds_bpermute_b32 v9, v15, v7
	ds_bpermute_b32 v16, v15, v4
	s_waitcnt lgkmcnt(1)
	v_add_f32_e32 v9, v4, v9
	v_max_f32_e32 v9, v9, v7
	v_cndmask_b32_e32 v7, v9, v7, vcc
	s_waitcnt lgkmcnt(0)
	v_add_f32_e32 v16, v4, v16
	ds_bpermute_b32 v9, v5, v7
	v_cndmask_b32_e32 v4, v16, v4, vcc
	ds_bpermute_b32 v5, v5, v4
	s_waitcnt lgkmcnt(1)
	v_add_f32_e32 v9, v4, v9
	v_max_f32_e32 v9, v9, v7
	s_waitcnt lgkmcnt(0)
	v_add_f32_e32 v5, v4, v5
	v_cndmask_b32_e64 v7, v9, v7, s[0:1]
	v_cndmask_b32_e64 v4, v5, v4, s[0:1]
	ds_bpermute_b32 v5, v11, v7
	ds_bpermute_b32 v9, v11, v4
	v_cmp_lt_i32_e64 s[0:1], v12, v3
	s_waitcnt lgkmcnt(1)
	v_add_f32_e32 v5, v4, v5
	v_cndmask_b32_e64 v11, v12, v2, s[0:1]
	v_max_f32_e32 v5, v5, v7
	v_cmp_gt_u32_e64 s[0:1], 4, v100
	v_lshlrev_b32_e32 v11, 2, v11
	s_waitcnt lgkmcnt(0)
	v_add_f32_e32 v9, v4, v9
	v_cndmask_b32_e64 v5, v5, v7, s[0:1]
	ds_bpermute_b32 v7, v11, v5
	v_cndmask_b32_e64 v4, v9, v4, s[0:1]
	ds_bpermute_b32 v9, v11, v4
	v_cmp_lt_i32_e64 s[0:1], v13, v3
	s_waitcnt lgkmcnt(1)
	v_add_f32_e32 v7, v4, v7
	v_cndmask_b32_e64 v11, v13, v2, s[0:1]
	v_max_f32_e32 v7, v7, v5
	v_cmp_gt_u32_e64 s[0:1], 8, v100
	v_lshlrev_b32_e32 v11, 2, v11
	s_waitcnt lgkmcnt(0)
	v_add_f32_e32 v9, v4, v9
	v_cndmask_b32_e64 v5, v7, v5, s[0:1]
	v_cndmask_b32_e64 v4, v9, v4, s[0:1]
	ds_bpermute_b32 v9, v11, v5
	ds_bpermute_b32 v7, v11, v4
	v_cmp_lt_i32_e64 s[0:1], v14, v3
	s_waitcnt lgkmcnt(1)
	v_add_f32_e32 v9, v4, v9
	v_cndmask_b32_e64 v3, v14, v2, s[0:1]
	v_max_f32_e32 v9, v9, v5
	v_cmp_gt_u32_e64 s[0:1], 16, v100
	v_lshlrev_b32_e32 v3, 2, v3
	s_waitcnt lgkmcnt(0)
	v_add_f32_e32 v7, v4, v7
	v_cndmask_b32_e64 v9, v9, v5, s[0:1]
	v_cndmask_b32_e64 v7, v7, v4, s[0:1]
	ds_bpermute_b32 v4, v3, v9
	ds_bpermute_b32 v5, v3, v7
	v_mul_lo_u32 v2, v10, s3
	v_max_f32_e32 v10, v9, v9
	v_cmp_gt_u32_e64 s[0:1], 32, v100
	s_waitcnt lgkmcnt(1)
	v_add_f32_e32 v11, v7, v4
	s_waitcnt lgkmcnt(0)
	v_add_f32_e32 v4, v7, v5
	v_max_f32_e32 v5, v11, v10
	v_cndmask_b32_e64 v9, v5, v9, s[0:1]
	v_cndmask_b32_e64 v7, v4, v7, s[0:1]
	ds_bpermute_b32 v7, v15, v7
	ds_bpermute_b32 v9, v15, v9
	v_ashrrev_i32_e32 v3, 31, v2
	v_lshl_add_u64 v[2:3], v[2:3], 2, s[70:71]
	v_lshl_add_u64 v[2:3], v[2:3], 0, s[4:5]
	v_lshl_add_u64 v[10:11], v[2:3], 0, v[0:1]
	v_max_f32_e32 v1, v8, v8
	s_waitcnt lgkmcnt(1)
	v_max_f32_e32 v7, v7, v7
	s_waitcnt lgkmcnt(0)
	v_max_f32_e32 v8, v9, v9
	v_max_f32_e32 v7, v7, v8
	v_cndmask_b32_e64 v8, v7, 0, vcc
	v_add_f32_e32 v6, v6, v8
	v_max_f32_e32 v9, v6, v1
	v_cmp_eq_u32_e32 vcc, 63, v100
	global_store_dwordx2 v[10:11], v[8:9], off
	s_and_saveexec_b64 s[0:1], vcc
	s_cbranch_execz .LBB0_437
	v_max_f32_e32 v1, v5, v5
	v_max_f32_e32 v4, v4, v4
	v_max_f32_e32 v1, v4, v1
	global_store_dword v[2:3], v1, off offset:512

; DI int fresh_tid() { int t = threadIdx.x; asm volatile("" : "+v"(t)); return t; }
; DI unsigned xb_ld(unsigned* p)              { return __hip_atomic_load(p, __ATOMIC_RELAXED, __HIP_MEMORY_SCOPE_AGENT); }
; DI unsigned xb_xcc_id() { return (unsigned)__builtin_amdgcn_s_getreg((3 << 11) | 20) & 0xFu; }
; DI void xcd_barrier_complete(unsigned* bar, unsigned x, unsigned& nloc, unsigned& nx) {
;     ...
;     for (;;) {
;         sum = 0u; cnt = 0u; mine = 0u;
; #pragma unroll
;         for (unsigned j = 0; j < 16; ++j) { const unsigned c = xb_ld(&bar[XB_XCNT(j)]); sum += c; cnt += (c > 0u) ? 1u : 0u; mine = (j == x) ? c : mine; }
; DI void xcd_barrier(unsigned* bar, volatile __attribute__((address_space(3))) unsigned* st) {
;     asm volatile("s_waitcnt vmcnt(0)" ::: "memory");
;     __syncthreads();
;     if (fresh_tid() == 0) {
;         __builtin_amdgcn_s_waitcnt(0);
;         const unsigned x = xb_xcc_id();
;         unsigned nloc = st[0], nx = st[1];
;         if (nloc == 0u) { xcd_barrier_complete(bar, x, nloc, nx); st[0] = nloc; st[1] = nx; }
.LBB0_472:
	s_waitcnt vmcnt(0)
	v_mov_b32_e32 v0, v250
	s_waitcnt vmcnt(0) lgkmcnt(0)
	s_barrier
	s_getpc_b64 vcc
	v_mov_b32_e32 v2, vcc_lo
	v_mov_b32_e32 v3, vcc_hi
	v_lshlrev_b32_e32 v1, 6, v0
	v_cmp_lt_u32_e32 vcc, 63, v0
	s_and_saveexec_b64 s[0:1], vcc
	s_cbranch_execz .Lcpf_s5
	v_add_co_u32_e32 v2, vcc, v2, v1
	s_nop 1
	v_addc_co_u32_e32 v3, vcc, 0, v3, vcc
	global_load_dword v4, v[2:3], off
.Lcpf_s5:
	s_or_b64 exec, exec, s[0:1]
	s_nop 0
	v_cmp_eq_u32_e32 vcc, 0, v0
	s_and_saveexec_b64 s[0:1], vcc
	s_cbranch_execz .LBB0_524
	v_mov_b32_e32 v0, 0
	s_waitcnt vmcnt(0) expcnt(0) lgkmcnt(0)
	s_getreg_b32 s3, hwreg(HW_REG_XCC_ID, 0, 4)
	ds_read_b32 v2, v0
	ds_read_b32 v1, v0 offset:4
	s_and_b32 s3, s3, 15
	s_waitcnt lgkmcnt(1)
	v_cmp_ne_u32_e32 vcc, 0, v2
	s_cbranch_vccnz .LBB0_488
	s_add_u32 s4, s70, 0x34e2300
	s_addc_u32 s5, s71, 0
	s_add_u32 s8, s70, 0x34e2500
	s_addc_u32 s9, s71, 0
	s_add_u32 s10, s70, 0x34e2600
	s_addc_u32 s11, s71, 0
	s_add_u32 s12, s70, 0x34e2700
	s_addc_u32 s13, s71, 0
	s_add_u32 s14, s70, 0x34e2800
	s_addc_u32 s15, s71, 0
	s_add_u32 s16, s70, 0x34e2900
	s_addc_u32 s17, s71, 0
	s_add_u32 s24, s70, 0x34e2a00
	s_addc_u32 s25, s71, 0
	s_add_u32 s26, s70, 0x34e2b00
	s_addc_u32 s27, s71, 0
	s_add_u32 s28, s70, 0x34e2c00
	s_addc_u32 s29, s71, 0
	s_add_u32 s30, s70, 0x34e2d00
	s_addc_u32 s31, s71, 0
	s_add_u32 s34, s70, 0x34e2e00
	s_addc_u32 s35, s71, 0
	s_add_u32 s36, s70, 0x34e2f00
	s_addc_u32 s37, s71, 0
	s_add_u32 s38, s70, 0x34e3000
	s_addc_u32 s39, s71, 0
	s_add_u32 s40, s70, 0x34e3100
	s_addc_u32 s41, s71, 0
	s_add_u32 s42, s70, 0x34e3200
	s_addc_u32 s43, s71, 0
	s_add_u32 s44, s70, 0x34e3300
	s_addc_u32 s45, s71, 0
	s_add_u32 s46, s70, 0x34e3400
	s_addc_u32 s47, s71, 0
	s_mov_b32 s55, 1
	s_branch .LBB0_476

; template <class LA, class LB>
; DI void gemm_tile(unsigned char* smem, const int tid, int nk, LA la, LB lb, f32x4 (&acc)[4][4]) {
;     const int lane = tid & 63, wid = tid >> 6;
;     const int wf = wid >> 1, wt = wid & 1;
;     const int lr = tid >> 3, lc = tid & 7;
;     unsigned char* sA = smem;
;     unsigned char* sB = smem + 32768;
; #pragma unroll
;     for (int i = 0; i < 4; ++i)
; #pragma unroll
;         for (int j = 0; j < 4; ++j) acc[i][j] = f32x4{0.f, 0.f, 0.f, 0.f};
;     uint4 ra[4], rb[4], na[4], nb[4];
; #pragma unroll
;     for (int i = 0; i < 4; ++i) { ra[i] = la(lr + 32 * i, lc * 8); rb[i] = lb(lr + 32 * i, lc * 8); }
;     if (nk > 1) {
; #pragma unroll
;         for (int i = 0; i < 4; ++i) { na[i] = la(lr + 32 * i, 64 + lc * 8); nb[i] = lb(lr + 32 * i, 64 + lc * 8); }
;     }
;     const int woff = lr * 128 + ((lc ^ ((lr >> 1) & 7)) << 4);
; #pragma unroll
;     for (int i = 0; i < 4; ++i) { *(uint4*)(sA + woff + i * 4096) = ra[i]; *(uint4*)(sB + woff + i * 4096) = rb[i]; }
; DI void phase5(const Params& p, unsigned char* smem, const int tid, const int vb, const int nvb) {
;     ...
;     for (int it = vb; it < 1024; it += nvb) {
;         const int g = it >> 5, mt = (it < 512) ? (7 - ((it >> 2) & 7)) : ((it >> 2) & 7), nt = it & 3;
;         const int ktz = 128 * (mt + 1);
;         const int nk = 2 * (mt + 1) + 2;
;         auto la = [=](int r, int kv) -> uint4 {
;             const int m = mt * 128 + r;
;             if (kv < ktz) {
;                 const int t = m >> 4, c = m & 15, j = kv >> 4, c0 = kv & 15;
;                 if (j > t) return make_uint4(0, 0, 0, 0);
;                 return *(const uint4*)(kc + (((size_t)(g * 64 + (t - j)) * 16 + c) * 16 + c0));
;             }
;             return *(const uint4*)(cmat + ((size_t)(g * 1024 + m)) * 128 + (kv - ktz));
;         };
;         auto lb = [=](int r, int kv) -> uint4 {
;             const int n = nt * 128 + r;
;             if (kv < ktz) return *(const uint4*)(us + ((size_t)g * 512 + n) * 1024 + kv);
;             return *(const uint4*)(xcar + ((size_t)n * 32 + g) * 128 + (kv - ktz));
;         };
;         f32x4 acc[4][4];
;         gemm_tile(smem, tid, nk, la, lb, acc);
.LBB0_524:
	s_or_b64 exec, exec, s[0:1]
	v_mov_b32_e32 v133, v250
	s_waitcnt lgkmcnt(0)
	s_waitcnt vmcnt(0)
	s_barrier
	s_movk_i32 s0, 0x400
	v_ashrrev_i32_e32 v0, 8, v133
	v_and_b32_e32 v136, 0xff, v133
	v_add_u32_e32 v138, s54, v0
	v_lshl_add_u32 v139, v0, 16, 16
	v_cmp_gt_i32_e32 vcc, s0, v138
	v_lshrrev_b32_e32 v140, 1, v136
	v_lshlrev_b32_e32 v137, 7, v136
	s_and_saveexec_b64 s[8:9], vcc
	s_cbranch_execz .LBB0_573
	v_and_b32_e32 v1, 7, v133
	v_lshlrev_b32_e32 v2, 2, v136
	v_and_b32_e32 v134, 0x1e0, v2
	v_mov_b32_e32 v135, 0
	v_lshlrev_b32_e32 v4, 4, v1
	v_lshl_add_u64 v[2:3], s[70:71], 0, v[134:135]
	v_and_b32_e32 v134, 16, v4
	v_lshl_add_u64 v[2:3], v[2:3], 0, v[134:135]
	s_mov_b64 s[0:1], 0x215c000
	v_lshrrev_b32_e32 v141, 3, v136
	v_lshl_add_u64 v[142:143], v[2:3], 0, s[0:1]
	v_lshlrev_b32_e32 v3, 4, v136
	v_lshlrev_b32_e32 v2, 7, v141
	v_xor_b32_e32 v3, v3, v133
	s_movk_i32 s0, 0x70
	v_and_b32_e32 v188, 64, v140
	v_and_or_b32 v2, v3, s0, v2
	v_and_or_b32 v5, v133, 15, v188
	v_add_u32_e32 v187, v139, v2
	v_bfe_u32 v2, v136, 1, 3
	v_bfe_u32 v3, v133, 4, 2
	v_lshl_add_u32 v189, v5, 7, v139
	v_and_b32_e32 v5, 0x2780, v137
	s_add_u32 s10, s70, 0x2a5c000
	v_add_u32_e32 v190, v139, v5
	v_bitop3_b32 v5, v140, v3, 7 bitop3:0x6c
	v_bitop3_b32 v2, v3, v2, 4 bitop3:0x36
	s_addc_u32 s11, s71, 0
	v_lshlrev_b32_e32 v132, 3, v1
	v_bfe_u32 v1, v1, 1, 28
	v_lshlrev_b32_e32 v191, 4, v5
	v_lshlrev_b32_e32 v192, 4, v2
	v_lshrrev_b32_e32 v2, 2, v133
	v_mov_b32_e32 v5, v135
	s_add_u32 s12, s68, 0x2800000
	v_and_b32_e32 v144, 12, v2
	v_lshl_add_u64 v[2:3], s[70:71], 0, v[4:5]
	s_mov_b64 s[0:1], 0x1c000100
	v_lshlrev_b32_e32 v0, 7, v0
	v_or_b32_e32 v195, 8, v1
	s_addc_u32 s13, s69, 0
	v_bfe_u32 v145, v133, 1, 2
	v_or_b32_e32 v183, 32, v141
	v_or_b32_e32 v184, 64, v141
	v_or_b32_e32 v185, 0x60, v141
	v_or_b32_e32 v186, 4, v1
	v_and_b32_e32 v193, 0x4f, v133
	v_lshl_add_u64 v[146:147], v[2:3], 0, s[0:1]
	v_lshl_add_u32 v194, s2, 8, v0
	s_lshl_b32 s38, s33, 8
	v_sub_u32_e32 v196, 0, v195
	s_mov_b64 s[14:15], 0
	s_movk_i32 s39, 0x200
	v_lshlrev_b32_e32 v148, 1, v132
	s_mov_b64 s[42:43], 0x100
	s_movk_i32 s40, 0x3ff
	v_mov_b32_e32 v149, v135
	v_mov_b32_e32 v197, v138
	s_branch .LBB0_527

; DI int fresh_tid() { int t = threadIdx.x; asm volatile("" : "+v"(t)); return t; }
; DI unsigned xb_ld(unsigned* p)              { return __hip_atomic_load(p, __ATOMIC_RELAXED, __HIP_MEMORY_SCOPE_AGENT); }
; DI unsigned xb_xcc_id() { return (unsigned)__builtin_amdgcn_s_getreg((3 << 11) | 20) & 0xFu; }
; DI void xcd_barrier_complete(unsigned* bar, unsigned x, unsigned& nloc, unsigned& nx) {
;     ...
;     for (;;) {
;         sum = 0u; cnt = 0u; mine = 0u;
; #pragma unroll
;         for (unsigned j = 0; j < 16; ++j) { const unsigned c = xb_ld(&bar[XB_XCNT(j)]); sum += c; cnt += (c > 0u) ? 1u : 0u; mine = (j == x) ? c : mine; }
; DI void xcd_barrier(unsigned* bar, volatile __attribute__((address_space(3))) unsigned* st) {
;     asm volatile("s_waitcnt vmcnt(0)" ::: "memory");
;     __syncthreads();
;     if (fresh_tid() == 0) {
;         __builtin_amdgcn_s_waitcnt(0);
;         const unsigned x = xb_xcc_id();
;         unsigned nloc = st[0], nx = st[1];
;         if (nloc == 0u) { xcd_barrier_complete(bar, x, nloc, nx); st[0] = nloc; st[1] = nx; }
.LBB0_580:
	s_or_b64 exec, exec, s[8:9]
	s_waitcnt vmcnt(0)
	v_mov_b32_e32 v0, v250
	s_barrier
	s_getpc_b64 vcc
	v_mov_b32_e32 v2, vcc_lo
	v_mov_b32_e32 v3, vcc_hi
	v_lshlrev_b32_e32 v1, 6, v0
	v_cmp_lt_u32_e32 vcc, 63, v0
	s_and_saveexec_b64 s[0:1], vcc
	s_cbranch_execz .Lcpf_s6
	v_add_co_u32_e32 v2, vcc, v2, v1
	s_nop 1
	v_addc_co_u32_e32 v3, vcc, 0, v3, vcc
	global_load_dword v4, v[2:3], off
.Lcpf_s6:
	s_or_b64 exec, exec, s[0:1]
	s_nop 0
	v_cmp_eq_u32_e32 vcc, 0, v0
	s_and_saveexec_b64 s[0:1], vcc
	s_cbranch_execz .LBB0_632
	v_mov_b32_e32 v0, 0
	s_waitcnt vmcnt(0) expcnt(0) lgkmcnt(0)
	s_getreg_b32 s3, hwreg(HW_REG_XCC_ID, 0, 4)
	ds_read_b32 v2, v0
	ds_read_b32 v1, v0 offset:4
	s_and_b32 s3, s3, 15
	s_waitcnt lgkmcnt(1)
	v_cmp_ne_u32_e32 vcc, 0, v2
	s_cbranch_vccnz .LBB0_596
	s_add_u32 s4, s70, 0x34e2300
	s_addc_u32 s5, s71, 0
	s_add_u32 s6, s70, 0x34e2500
	s_addc_u32 s7, s71, 0
	s_add_u32 s8, s70, 0x34e2600
	s_addc_u32 s9, s71, 0
	s_add_u32 s10, s70, 0x34e2700
	s_addc_u32 s11, s71, 0
	s_add_u32 s12, s70, 0x34e2800
	s_addc_u32 s13, s71, 0
	s_add_u32 s14, s70, 0x34e2900
	s_addc_u32 s15, s71, 0
	s_add_u32 s16, s70, 0x34e2a00
	s_addc_u32 s17, s71, 0
	s_add_u32 s24, s70, 0x34e2b00
	s_addc_u32 s25, s71, 0
	s_add_u32 s26, s70, 0x34e2c00
	s_addc_u32 s27, s71, 0
	s_add_u32 s28, s70, 0x34e2d00
	s_addc_u32 s29, s71, 0
	s_add_u32 s30, s70, 0x34e2e00
	s_addc_u32 s31, s71, 0
	s_add_u32 s34, s70, 0x34e2f00
	s_addc_u32 s35, s71, 0
	s_add_u32 s36, s70, 0x34e3000
	s_addc_u32 s37, s71, 0
	s_add_u32 s38, s70, 0x34e3100
	s_addc_u32 s39, s71, 0
	s_add_u32 s40, s70, 0x34e3200
	s_addc_u32 s41, s71, 0
	s_add_u32 s42, s70, 0x34e3300
	s_addc_u32 s43, s71, 0
	s_add_u32 s44, s70, 0x34e3400
	s_addc_u32 s45, s71, 0
	s_mov_b32 s52, 1
	s_branch .LBB0_584

; DI int fresh_tid() { int t = threadIdx.x; asm volatile("" : "+v"(t)); return t; }
; DI void phase6_scan(const Params& p) {
;     unsigned char* ws = p.ws;
;     const int tid = fresh_tid();
;     for (int it = blockIdx.x; it < 256; it += gridDim.x) {
;         const int e4 = it * 512 + tid;
;         const int bh = e4 >> 13;
;         const size_t off = (size_t)(e4 & 8191) * 4;
;         bf16_t* base = (bf16_t*)(ws + 1 * U_) + (size_t)bh * 128 * 32768 + off;
;         const float* bl = (const float*)(ws + OFF_BLAST) + bh * 128;
;         const float* ms = (const float*)(ws + OFF_MST) + bh * 132;
;         float C[4] = {0.f, 0.f, 0.f, 0.f};
;         uint2 nxt[16];
; #pragma unroll
;         for (int i = 0; i < 16; ++i) nxt[i] = *(const uint2*)(base + (size_t)i * 32768);
.LBB0_632:
	s_or_b64 exec, exec, s[0:1]
	v_mov_b32_e32 v109, v250
	s_cmpk_gt_i32 s2, 0xff
	s_waitcnt lgkmcnt(0)
	s_waitcnt vmcnt(0)
	s_barrier
	s_cbranch_scc1 .LBB0_635
	s_add_u32 s0, s70, 0x33de000
	s_addc_u32 s1, s71, 0
	s_add_u32 s4, s70, 0x33e0000
	v_lshlrev_b32_e32 v0, 2, v109
	v_readlane_b32 s3, v254, 53
	v_mov_b32_e32 v1, 0
	s_addc_u32 s5, s71, 0
	v_lshl_add_u32 v111, s2, 11, v0
	s_lshl_b32 s6, s33, 11
	v_add_u32_e32 v113, s3, v109
	s_lshl_b32 s7, s33, 9
	v_mov_b32_e32 v116, v1
	v_mov_b32_e32 v117, v1
	s_mov_b32 s8, 0x560000
	s_mov_b32 s9, 0x570000
	s_mov_b32 s10, 0x580000
	s_mov_b32 s11, 0x590000
	s_mov_b32 s12, 0x5a0000
	s_mov_b32 s13, 0x5b0000
	s_mov_b32 s14, 0x5c0000
	s_mov_b32 s15, 0x5d0000
	s_mov_b32 s16, 0x5e0000
	s_mov_b32 s17, 0x5f0000
	s_mov_b32 s24, 0x600000
	s_mov_b32 s25, 0x610000
	s_mov_b32 s26, 0x620000
	s_mov_b32 s27, 0x630000
	s_mov_b32 s28, 0x640000
	s_mov_b32 s29, 0x650000
	s_mov_b32 s30, 0x660000
	s_mov_b32 s31, 0x670000
	s_mov_b32 s34, 0x680000
	s_mov_b32 s35, 0x690000
	s_mov_b32 s36, 0x6a0000
	s_mov_b32 s37, 0x6b0000
	s_mov_b32 s38, 0x6c0000
	s_mov_b32 s39, 0x6d0000
	s_mov_b32 s40, 0x6e0000
	s_mov_b32 s41, 0x6f0000
	s_mov_b32 s42, 0x700000
	s_mov_b32 s43, 0x710000
	s_mov_b32 s44, 0x720000
	s_mov_b32 s45, 0x730000
	s_mov_b32 s46, 0x740000
	s_mov_b32 s47, 0x750000
	s_mov_b32 s48, 0x760000
	s_mov_b32 s49, 0x770000
	s_mov_b32 s50, 0x780000
	s_mov_b32 s51, 0x790000
	s_mov_b32 s52, 0x7a0000
	s_mov_b32 s53, 0x7b0000
	s_mov_b32 s55, 0x7c0000
	s_mov_b32 s56, 0x7d0000
	s_mov_b32 s57, 0x7e0000
	s_mov_b32 s86, s2

; DI int fresh_tid() { int t = threadIdx.x; asm volatile("" : "+v"(t)); return t; }
; DI unsigned xb_ld(unsigned* p)              { return __hip_atomic_load(p, __ATOMIC_RELAXED, __HIP_MEMORY_SCOPE_AGENT); }
; DI unsigned xb_xcc_id() { return (unsigned)__builtin_amdgcn_s_getreg((3 << 11) | 20) & 0xFu; }
; DI void xcd_barrier_complete(unsigned* bar, unsigned x, unsigned& nloc, unsigned& nx) {
;     ...
;     for (;;) {
;         sum = 0u; cnt = 0u; mine = 0u;
; #pragma unroll
;         for (unsigned j = 0; j < 16; ++j) { const unsigned c = xb_ld(&bar[XB_XCNT(j)]); sum += c; cnt += (c > 0u) ? 1u : 0u; mine = (j == x) ? c : mine; }
; DI void xcd_barrier(unsigned* bar, volatile __attribute__((address_space(3))) unsigned* st) {
;     asm volatile("s_waitcnt vmcnt(0)" ::: "memory");
;     __syncthreads();
;     if (fresh_tid() == 0) {
;         __builtin_amdgcn_s_waitcnt(0);
;         const unsigned x = xb_xcc_id();
;         unsigned nloc = st[0], nx = st[1];
;         if (nloc == 0u) { xcd_barrier_complete(bar, x, nloc, nx); st[0] = nloc; st[1] = nx; }
.LBB0_662:
	s_waitcnt vmcnt(0)
	v_mov_b32_e32 v0, v250
	s_waitcnt vmcnt(0)
	s_barrier
	s_getpc_b64 vcc
	v_mov_b32_e32 v2, vcc_lo
	v_mov_b32_e32 v3, vcc_hi
	v_lshlrev_b32_e32 v1, 6, v0
	v_cmp_lt_u32_e32 vcc, 63, v0
	s_and_saveexec_b64 s[0:1], vcc
	s_cbranch_execz .Lcpf_s7
	v_add_co_u32_e32 v2, vcc, v2, v1
	s_nop 1
	v_addc_co_u32_e32 v3, vcc, 0, v3, vcc
	global_load_dword v4, v[2:3], off
.Lcpf_s7:
	s_or_b64 exec, exec, s[0:1]
	s_nop 0
	v_cmp_eq_u32_e32 vcc, 0, v0
	s_and_saveexec_b64 s[0:1], vcc
	s_cbranch_execz .LBB0_714
	v_mov_b32_e32 v0, 0
	s_waitcnt vmcnt(0) expcnt(0) lgkmcnt(0)
	s_getreg_b32 s3, hwreg(HW_REG_XCC_ID, 0, 4)
	ds_read_b32 v2, v0
	ds_read_b32 v1, v0 offset:4
	s_and_b32 s3, s3, 15
	s_waitcnt lgkmcnt(1)
	v_cmp_ne_u32_e32 vcc, 0, v2
	s_cbranch_vccnz .LBB0_678
	s_add_u32 s4, s70, 0x34e2300
	s_addc_u32 s5, s71, 0
	s_add_u32 s6, s70, 0x34e2500
	s_addc_u32 s7, s71, 0
	s_add_u32 s8, s70, 0x34e2600
	s_addc_u32 s9, s71, 0
	s_add_u32 s10, s70, 0x34e2700
	s_addc_u32 s11, s71, 0
	s_add_u32 s12, s70, 0x34e2800
	s_addc_u32 s13, s71, 0
	s_add_u32 s14, s70, 0x34e2900
	s_addc_u32 s15, s71, 0
	s_add_u32 s16, s70, 0x34e2a00
	s_addc_u32 s17, s71, 0
	s_add_u32 s18, s70, 0x34e2b00
	s_addc_u32 s19, s71, 0
	s_add_u32 s24, s70, 0x34e2c00
	s_addc_u32 s25, s71, 0
	s_add_u32 s26, s70, 0x34e2d00
	s_addc_u32 s27, s71, 0
	s_add_u32 s28, s70, 0x34e2e00
	s_addc_u32 s29, s71, 0
	s_add_u32 s30, s70, 0x34e2f00
	s_addc_u32 s31, s71, 0
	s_add_u32 s34, s70, 0x34e3000
	s_addc_u32 s35, s71, 0
	s_add_u32 s36, s70, 0x34e3100
	s_addc_u32 s37, s71, 0
	s_add_u32 s38, s70, 0x34e3200
	s_addc_u32 s39, s71, 0
	s_add_u32 s40, s70, 0x34e3300
	s_addc_u32 s41, s71, 0
	s_add_u32 s42, s70, 0x34e3400
	s_addc_u32 s43, s71, 0
	s_mov_b32 s50, 1
	s_branch .LBB0_666

; DI void mlstm_out_unit(const Params& p, unsigned char* smem, const int tid, int u) {
;     ...
;         const int i16 = lane & 15;
;         const bf16_t* ctb0 = CT + (((size_t)bh * 128 + c) * 256 + 64 * w + (i16 >> 2) * 8 + (i16 & 3)) * 128 + (lane >> 4) * 8;
; #pragma unroll
;         for (int ks = 0; ks < 4; ++ks)
; #pragma unroll
;             for (int i = 0; i < 4; ++i) ctf[ks][i] = ld16(ctb0 + (size_t)((i >> 1) * 32 + (i & 1) * 4) * 128 + ks * 32);
;     }
;     if (w == 0) {
;         float bj = ((const float*)(ws + OFF_BCUM))[tok0 + lane], ij = ((const float*)(ws + OFF_IG))[tok0 + lane];
;         float g = ij - bj, pm = g;
;         for (int d = 1; d < 64; d <<= 1) { float o = __shfl_up(pm, d, 64); if (lane >= d) pm = fmaxf(pm, o); }
;         float mt = bj + fmaxf(mc, pm);
;         gk[lane] = g; bq[lane] = bj - mt; sci[lane] = __expf(bj + mc - mt); emt[lane] = __expf(-mt);
;     }
;     {
;         const int t = tid >> 2, p4 = tid & 3;
;         const bf16_t* qr = q + (tok0 + t) * 128 + p4 * 32;
;         const float* nr = (const float*)(ws + OFF_NU) + ((size_t)bh * 128 + c) * 128 + p4 * 32;
;         float s = 0.f;
; #pragma unroll
;         for (int i = 0; i < 4; ++i) {
;             uint4 a = *(const uint4*)(qr + i * 8);
;             const unsigned* pa = (const unsigned*)&a;
; #pragma unroll
;             for (int e = 0; e < 4; ++e) s += bf2f(pa[e] & 0xffff) * nr[i * 8 + 2 * e] + bf2f(pa[e] >> 16) * nr[i * 8 + 2 * e + 1];
;         }
;         s += __shfl_xor(s, 1, 64); s += __shfl_xor(s, 2, 64);
;         if (p4 == 0) qn[t] = s;
;     }
;     __syncthreads();
;     {
;         f32x4 X[4];
; #pragma unroll
;         for (int jt = 0; jt < 4; ++jt) X[jt] = f32x4{0.f, 0.f, 0.f, 0.f};
;         const bf16_t* qb = q + (tok0 + 16 * w + (lane & 15)) * 128 + (lane >> 4) * 8;
;         bf16x8 qf[4];
; #pragma unroll
;         for (int ks = 0; ks < 4; ++ks) qf[ks] = ld16(qb + ks * 32);
; #pragma unroll
;         for (int jt = 0; jt < 4; ++jt) {
;             if (jt <= w) {
;                 const bf16_t* kb = k + (tok0 + 16 * jt + (lane & 15)) * 128 + (lane >> 4) * 8;
; #pragma unroll
;                 for (int ks = 0; ks < 4; ++ks) X[jt] = mfma16(ld16(kb + ks * 32), qf[ks], X[jt]);
;             }
;         }
;         const int t = 16 * w + (lane & 15);
;         const float bqt = bq[t];
;         float dsum = 0.f;
; #pragma unroll
.LBB0_714:
	s_or_b64 exec, exec, s[0:1]
	v_mov_b32_e32 v0, v250
	s_waitcnt lgkmcnt(0)
	s_waitcnt vmcnt(0)
	s_barrier
	s_movk_i32 s0, 0x800
	v_ashrrev_i32_e32 v1, 8, v0
	v_add_u32_e32 v97, s54, v1
	v_cmp_gt_i32_e32 vcc, s0, v97
	s_mov_b64 s[0:1], exec
	v_writelane_b32 v255, s0, 2
	s_nop 1
	v_writelane_b32 v255, s1, 3
	s_and_b64 s[0:1], s[0:1], vcc
	s_mov_b64 exec, s[0:1]
	s_cbranch_execz .LBB0_783
	v_lshlrev_b32_e32 v2, 1, v0
	v_and_b32_e32 v7, 0xc0, v0
	v_and_b32_e32 v2, 24, v2
	v_and_b32_e32 v8, 3, v0
	v_lshl_add_u32 v1, v1, 16, 16
	v_and_b32_e32 v6, 0xff, v0
	v_and_b32_e32 v96, 63, v0
	v_or3_b32 v98, v7, v2, v8
	v_mov_b32_e32 v101, 0
	v_bfe_u32 v9, v0, 4, 2
	v_and_b32_e32 v2, 48, v0
	v_readlane_b32 s0, v254, 62
	v_bfe_u32 v10, v0, 6, 2
	v_and_b32_e32 v104, 15, v0
	v_bfe_u32 v106, v0, 2, 6
	v_and_b32_e32 v0, 0xfc, v0
	v_mov_b32_e32 v3, v101
	v_readlane_b32 s1, v254, 63
	v_add_u32_e32 v105, v1, v0
	v_lshlrev_b32_e32 v0, 2, v9
	v_lshl_add_u64 v[102:103], s[0:1], 0, v[2:3]
	v_lshl_add_u64 v[112:113], s[76:77], 0, v[2:3]
	v_lshl_add_u64 v[114:115], s[78:79], 0, v[2:3]
	v_lshl_or_b32 v116, v10, 4, v104
	v_add_u32_e32 v117, v1, v2
	v_or_b32_e32 v2, 2, v0
	v_cmp_le_u32_e64 s[26:27], v2, v116
	v_or_b32_e32 v2, 3, v0
	v_cmp_le_u32_e64 s[28:29], v2, v116
	v_or_b32_e32 v2, 16, v0
	v_cmp_le_u32_e64 s[30:31], v2, v116
	v_or_b32_e32 v2, 17, v0
	v_cmp_le_u32_e64 s[34:35], v2, v116
	v_or_b32_e32 v2, 18, v0
	v_cmp_le_u32_e64 s[36:37], v2, v116
	v_or_b32_e32 v2, 19, v0
	v_cmp_le_u32_e64 s[38:39], v2, v116
	v_or_b32_e32 v2, 32, v0
	v_cmp_le_u32_e64 s[40:41], v2, v116
	v_or_b32_e32 v2, 33, v0
	v_cmp_le_u32_e64 s[42:43], v2, v116
	v_or_b32_e32 v2, 34, v0
	v_cmp_le_u32_e64 s[44:45], v2, v116
	v_or_b32_e32 v2, 35, v0
	v_cmp_le_u32_e64 s[46:47], v2, v116
	v_or_b32_e32 v2, 48, v0
	v_cmp_le_u32_e64 s[48:49], v2, v116
	v_or_b32_e32 v2, 49, v0
	v_cmp_le_u32_e64 s[22:23], v0, v116
	v_cmp_lt_u32_e64 s[24:25], v0, v116
	v_cmp_le_u32_e64 s[50:51], v2, v116
	v_or_b32_e32 v2, 50, v0
	v_or_b32_e32 v0, 51, v0
	s_add_u32 s94, s70, 0x33e0000
	v_lshlrev_b32_e32 v4, 6, v8
	v_mov_b32_e32 v5, v101
	v_cmp_le_u32_e64 s[54:55], v0, v116
	v_mov_b32_e32 v0, 0x1c00
	s_addc_u32 s95, s71, 0
	v_cmp_eq_u32_e64 s[4:5], 0, v96
	v_lshl_add_u64 v[108:109], s[76:77], 0, v[4:5]
	v_lshlrev_b32_e32 v4, 7, v8
	v_lshl_or_b32 v0, v6, 4, v0
	v_lshlrev_b32_e32 v100, 3, v9
	s_add_u32 s96, s70, 0x335c000
	v_writelane_b32 v254, s4, 0
	v_lshl_add_u64 v[4:5], s[70:71], 0, v[4:5]
	s_mov_b64 s[16:17], 0x33e2100
	s_movk_i32 s3, 0x7f
	v_lshl_add_u32 v119, v96, 4, v1
	v_add_u32_e32 v134, v1, v0
	v_mbcnt_lo_u32_b32 v0, -1, 0
	v_cmp_gt_u32_e64 s[0:1], 64, v6
	v_cmp_lt_u32_e64 s[56:57], 63, v6
	s_addc_u32 s97, s71, 0
	v_writelane_b32 v254, s5, 1
	v_cmp_gt_u32_e64 s[6:7], 2, v96
	v_cmp_gt_u32_e64 s[8:9], 4, v96
	v_cmp_gt_u32_e64 s[10:11], 8, v96
	v_cmp_gt_u32_e64 s[12:13], 16, v96
	v_cmp_gt_u32_e64 s[14:15], 32, v96
	v_lshl_add_u32 v99, v96, 2, v1
	v_lshl_add_u64 v[110:111], v[4:5], 0, s[16:17]
	v_cmp_eq_u32_e64 s[16:17], 0, v8
	v_cmp_lt_u32_e64 s[18:19], s3, v6
	v_cmp_eq_u32_e64 s[20:21], 3, v10
	v_lshl_add_u32 v107, v116, 2, v1
	v_cmp_le_u32_e64 s[52:53], v2, v116
	v_lshl_add_u32 v121, v10, 11, v119
	v_or_b32_e32 v118, 16, v104
	v_lshl_add_u32 v123, v104, 2, v1
	v_or_b32_e32 v120, 32, v104
	v_or_b32_e32 v122, 48, v104
	v_lshl_add_u64 v[124:125], s[92:93], 0, v[100:101]
	v_lshl_add_u32 v135, v6, 2, v1
	v_or_b32_e32 v136, v100, v7
	s_mov_b64 s[92:93], 0
	s_movk_i32 s91, 0x2000
	s_movk_i32 s3, 0x1000
	v_mov_b32_e32 v137, 0x3727c5ac
	v_mbcnt_hi_u32_b32 v138, -1, v0
	s_branch .LBB0_717

; DI int fresh_tid() { int t = threadIdx.x; asm volatile("" : "+v"(t)); return t; }
; DI unsigned xb_ld(unsigned* p)              { return __hip_atomic_load(p, __ATOMIC_RELAXED, __HIP_MEMORY_SCOPE_AGENT); }
; DI unsigned xb_xcc_id() { return (unsigned)__builtin_amdgcn_s_getreg((3 << 11) | 20) & 0xFu; }
; DI void xcd_barrier_complete(unsigned* bar, unsigned x, unsigned& nloc, unsigned& nx) {
;     ...
;     for (;;) {
;         sum = 0u; cnt = 0u; mine = 0u;
; #pragma unroll
;         for (unsigned j = 0; j < 16; ++j) { const unsigned c = xb_ld(&bar[XB_XCNT(j)]); sum += c; cnt += (c > 0u) ? 1u : 0u; mine = (j == x) ? c : mine; }
; DI void xcd_barrier(unsigned* bar, volatile __attribute__((address_space(3))) unsigned* st) {
;     asm volatile("s_waitcnt vmcnt(0)" ::: "memory");
;     __syncthreads();
;     if (fresh_tid() == 0) {
;         __builtin_amdgcn_s_waitcnt(0);
;         const unsigned x = xb_xcc_id();
;         unsigned nloc = st[0], nx = st[1];
;         if (nloc == 0u) { xcd_barrier_complete(bar, x, nloc, nx); st[0] = nloc; st[1] = nx; }
.LBB0_783:
	v_readlane_b32 s0, v255, 2
	v_readlane_b32 s1, v255, 3
	s_or_b64 exec, exec, s[0:1]
	s_waitcnt vmcnt(0)
	v_mov_b32_e32 v0, v250
	s_barrier
	s_getpc_b64 vcc
	v_mov_b32_e32 v2, vcc_lo
	v_mov_b32_e32 v3, vcc_hi
	v_lshlrev_b32_e32 v1, 6, v0
	v_cmp_lt_u32_e32 vcc, 63, v0
	s_and_saveexec_b64 s[0:1], vcc
	s_cbranch_execz .Lcpf_s8
	v_add_co_u32_e32 v2, vcc, v2, v1
	s_nop 1
	v_addc_co_u32_e32 v3, vcc, 0, v3, vcc
	global_load_dword v4, v[2:3], off
.Lcpf_s8:
	s_or_b64 exec, exec, s[0:1]
	s_nop 0
	v_cmp_eq_u32_e32 vcc, 0, v0
	s_and_saveexec_b64 s[0:1], vcc
	v_readlane_b32 s96, v254, 62
	v_readlane_b32 s97, v254, 63
	s_cbranch_execz .LBB0_835
	v_mov_b32_e32 v0, 0
	s_waitcnt vmcnt(0) expcnt(0) lgkmcnt(0)
	s_getreg_b32 s3, hwreg(HW_REG_XCC_ID, 0, 4)
	ds_read_b32 v2, v0
	ds_read_b32 v1, v0 offset:4
	s_and_b32 s3, s3, 15
	s_waitcnt lgkmcnt(1)
	v_cmp_ne_u32_e32 vcc, 0, v2
	s_cbranch_vccnz .LBB0_799
	s_add_u32 s4, s70, 0x34e2300
	s_addc_u32 s5, s71, 0
	s_add_u32 s6, s70, 0x34e2500
	s_addc_u32 s7, s71, 0
	s_add_u32 s8, s70, 0x34e2600
	s_addc_u32 s9, s71, 0
	s_add_u32 s10, s70, 0x34e2700
	s_addc_u32 s11, s71, 0
	s_add_u32 s12, s70, 0x34e2800
	s_addc_u32 s13, s71, 0
	s_add_u32 s14, s70, 0x34e2900
	s_addc_u32 s15, s71, 0
	s_add_u32 s16, s70, 0x34e2a00
	s_addc_u32 s17, s71, 0
	s_add_u32 s18, s70, 0x34e2b00
	s_addc_u32 s19, s71, 0
	s_add_u32 s20, s70, 0x34e2c00
	s_addc_u32 s21, s71, 0
	s_add_u32 s22, s70, 0x34e2d00
	s_addc_u32 s23, s71, 0
	s_add_u32 s24, s70, 0x34e2e00
	s_addc_u32 s25, s71, 0
	s_add_u32 s26, s70, 0x34e2f00
	s_addc_u32 s27, s71, 0
	s_add_u32 s28, s70, 0x34e3000
	s_addc_u32 s29, s71, 0
	s_add_u32 s30, s70, 0x34e3100
	s_addc_u32 s31, s71, 0
	s_add_u32 s34, s70, 0x34e3200
	s_addc_u32 s35, s71, 0
	s_add_u32 s36, s70, 0x34e3300
	s_addc_u32 s37, s71, 0
	s_add_u32 s38, s70, 0x34e3400
	s_addc_u32 s39, s71, 0
	s_mov_b32 s46, 1
	s_branch .LBB0_787

;     DI bool next(int i, Unit& u) const {
;         const long L = (long)i * G + c; if (L >= nwg) return false;
;         int wgid = (int)L; { const int q = nwg / NXCD, r = nwg % NXCD, xcd = wgid % NXCD, off = wgid / NXCD; wgid = (xcd < r ? xcd * (q + 1) : r * (q + 1) + (xcd - r) * q) + off; }
;         const int nig = WGM * nN, gid = wgid / nig, fm = gid * WGM, gsz = (nM - fm) < WGM ? (nM - fm) : WGM;
;         u.pm = fm + ((wgid % nig) % gsz); u.pn = (wgid % nig) / gsz; return true;
; __global__ void __launch_bounds__(512, 2) fwd_megakernel(Params p) {
;     ...
;     {
;         pg8::Gemm g{(const bf16_t*)p.out, (const bf16_t*)(ws + OFF_WDN), 1024, 1024, 1024, 0};
;         S.init(T_, 1024, gridDim.x, blockIdx.x);
;         EpiDown E{(const unsigned char*)(ws + 5 * U_), (const unsigned char*)(ws + 6 * U_), (const bf16_t*)(ws + 7 * U_), (bf16_t*)(ws + 1 * U_)};
;         pg8::gemm_phase(glds, g, S, E);
.LBB0_835:
	s_or_b64 exec, exec, s[0:1]
	v_readlane_b32 s4, v254, 60
	v_readlane_b32 s5, v254, 61
	v_mov_b32_e32 v8, v250
	s_waitcnt lgkmcnt(0)
	v_cndmask_b32_e64 v0, 0, 1, s[4:5]
	s_waitcnt vmcnt(0)
	s_barrier
	v_cmp_ne_u32_e64 s[0:1], 1, v0
	s_andn2_b64 vcc, exec, s[4:5]
	v_readfirstlane_b32 s9, v8
	s_cbranch_vccnz .LBB0_859
	s_ashr_i32 s3, s2, 31
	s_lshr_b32 s4, s3, 29
	s_add_i32 s7, s2, s4
	s_and_b32 s4, s7, -8
	s_sub_i32 s8, s2, s4
	s_cmp_gt_i32 s8, -1
	s_cbranch_scc0 .LBB0_838
	s_lshl_b32 s6, s8, 6
	s_cbranch_execz .LBB0_839
	s_branch .LBB0_840

; DI int fresh_tid() { int t = threadIdx.x; asm volatile("" : "+v"(t)); return t; }
; DI unsigned xb_ld(unsigned* p)              { return __hip_atomic_load(p, __ATOMIC_RELAXED, __HIP_MEMORY_SCOPE_AGENT); }
; DI unsigned xb_xcc_id() { return (unsigned)__builtin_amdgcn_s_getreg((3 << 11) | 20) & 0xFu; }
; DI void xcd_barrier_complete(unsigned* bar, unsigned x, unsigned& nloc, unsigned& nx) {
;     ...
;     for (;;) {
;         sum = 0u; cnt = 0u; mine = 0u;
; #pragma unroll
;         for (unsigned j = 0; j < 16; ++j) { const unsigned c = xb_ld(&bar[XB_XCNT(j)]); sum += c; cnt += (c > 0u) ? 1u : 0u; mine = (j == x) ? c : mine; }
; DI void xcd_barrier(unsigned* bar, volatile __attribute__((address_space(3))) unsigned* st) {
;     asm volatile("s_waitcnt vmcnt(0)" ::: "memory");
;     __syncthreads();
;     if (fresh_tid() == 0) {
;         __builtin_amdgcn_s_waitcnt(0);
;         const unsigned x = xb_xcc_id();
;         unsigned nloc = st[0], nx = st[1];
;         if (nloc == 0u) { xcd_barrier_complete(bar, x, nloc, nx); st[0] = nloc; st[1] = nx; }
.LBB0_859:
	s_waitcnt vmcnt(0)
	v_mov_b32_e32 v0, v250
	s_barrier
	s_getpc_b64 vcc
	v_mov_b32_e32 v2, vcc_lo
	v_mov_b32_e32 v3, vcc_hi
	v_lshlrev_b32_e32 v1, 6, v0
	v_cmp_lt_u32_e32 vcc, 63, v0
	s_and_saveexec_b64 s[4:5], vcc
	s_cbranch_execz .Lcpf_s9
	v_add_co_u32_e32 v2, vcc, v2, v1
	s_nop 1
	v_addc_co_u32_e32 v3, vcc, 0, v3, vcc
	global_load_dword v4, v[2:3], off
.Lcpf_s9:
	s_or_b64 exec, exec, s[4:5]
	s_nop 0
	v_cmp_eq_u32_e32 vcc, 0, v0
	s_and_saveexec_b64 s[4:5], vcc
	v_readlane_b32 s50, v254, 54
	v_readlane_b32 s51, v254, 55
	s_cbranch_execz .LBB0_911
	v_mov_b32_e32 v0, 0
	s_waitcnt vmcnt(0) expcnt(0) lgkmcnt(0)
	s_getreg_b32 s3, hwreg(HW_REG_XCC_ID, 0, 4)
	ds_read_b32 v2, v0
	ds_read_b32 v1, v0 offset:4
	s_and_b32 s3, s3, 15
	s_waitcnt lgkmcnt(1)
	v_cmp_ne_u32_e32 vcc, 0, v2
	s_cbranch_vccnz .LBB0_875
	s_add_u32 s6, s70, 0x34e2300
	s_addc_u32 s7, s71, 0
	s_add_u32 s8, s70, 0x34e2500
	s_addc_u32 s9, s71, 0
	s_add_u32 s10, s70, 0x34e2600
	s_addc_u32 s11, s71, 0
	s_add_u32 s12, s70, 0x34e2700
	s_addc_u32 s13, s71, 0
	s_add_u32 s14, s70, 0x34e2800
	s_addc_u32 s15, s71, 0
	s_add_u32 s16, s70, 0x34e2900
	s_addc_u32 s17, s71, 0
	s_add_u32 s18, s70, 0x34e2a00
	s_addc_u32 s19, s71, 0
	s_add_u32 s20, s70, 0x34e2b00
	s_addc_u32 s21, s71, 0
	s_add_u32 s22, s70, 0x34e2c00
	s_addc_u32 s23, s71, 0
	s_add_u32 s24, s70, 0x34e2d00
	s_addc_u32 s25, s71, 0
	s_add_u32 s26, s70, 0x34e2e00
	s_addc_u32 s27, s71, 0
	s_add_u32 s28, s70, 0x34e2f00
	s_addc_u32 s29, s71, 0
	s_add_u32 s30, s70, 0x34e3000
	s_addc_u32 s31, s71, 0
	s_add_u32 s34, s70, 0x34e3100
	s_addc_u32 s35, s71, 0
	s_add_u32 s36, s70, 0x34e3200
	s_addc_u32 s37, s71, 0
	s_add_u32 s38, s70, 0x34e3300
	s_addc_u32 s39, s71, 0
	s_add_u32 s40, s70, 0x34e3400
	s_addc_u32 s41, s71, 0
	s_mov_b32 s48, 1
	s_branch .LBB0_863

;     DI bool next(int i, Unit& u) const {
;         const long L = (long)i * G + c; if (L >= nwg) return false;
;         int wgid = (int)L; { const int q = nwg / NXCD, r = nwg % NXCD, xcd = wgid % NXCD, off = wgid / NXCD; wgid = (xcd < r ? xcd * (q + 1) : r * (q + 1) + (xcd - r) * q) + off; }
;         const int nig = WGM * nN, gid = wgid / nig, fm = gid * WGM, gsz = (nM - fm) < WGM ? (nM - fm) : WGM;
;         u.pm = fm + ((wgid % nig) % gsz); u.pn = (wgid % nig) / gsz; return true;
; __global__ void __launch_bounds__(512, 2) fwd_megakernel(Params p) {
;     ...
;     {
;         pg8::Gemm g{(const bf16_t*)(ws + 1 * U_), (const bf16_t*)(ws + OFF_WMX), 1024, 1024, 1024, 0};
;         S.init(T_, 1024, gridDim.x, blockIdx.x);
;         EpiRes E{p.in[0], (const float*)(ws + OFF_MOD) + 2048, (bf16_t*)(ws + 2 * U_)};
;         pg8::gemm_phase(glds, g, S, E);
.LBB0_911:
	s_or_b64 exec, exec, s[4:5]
	v_mov_b32_e32 v9, v250
	s_waitcnt lgkmcnt(0)
	s_waitcnt vmcnt(0)
	s_barrier
	s_and_b64 vcc, exec, s[0:1]
	v_readfirstlane_b32 s12, v9
	s_cbranch_vccnz .LBB0_935
	s_ashr_i32 s3, s2, 31
	s_lshr_b32 s4, s3, 29
	s_add_i32 s7, s2, s4
	s_and_b32 s4, s7, -8
	s_sub_i32 s8, s2, s4
	s_cmp_gt_i32 s8, -1
	s_cbranch_scc0 .LBB0_914
	s_lshl_b32 s6, s8, 6
	s_cbranch_execz .LBB0_915
	s_branch .LBB0_916

; DI int fresh_tid() { int t = threadIdx.x; asm volatile("" : "+v"(t)); return t; }
; DI unsigned xb_ld(unsigned* p)              { return __hip_atomic_load(p, __ATOMIC_RELAXED, __HIP_MEMORY_SCOPE_AGENT); }
; DI unsigned xb_xcc_id() { return (unsigned)__builtin_amdgcn_s_getreg((3 << 11) | 20) & 0xFu; }
; DI void xcd_barrier_complete(unsigned* bar, unsigned x, unsigned& nloc, unsigned& nx) {
;     ...
;     for (;;) {
;         sum = 0u; cnt = 0u; mine = 0u;
; #pragma unroll
;         for (unsigned j = 0; j < 16; ++j) { const unsigned c = xb_ld(&bar[XB_XCNT(j)]); sum += c; cnt += (c > 0u) ? 1u : 0u; mine = (j == x) ? c : mine; }
; DI void xcd_barrier(unsigned* bar, volatile __attribute__((address_space(3))) unsigned* st) {
;     asm volatile("s_waitcnt vmcnt(0)" ::: "memory");
;     __syncthreads();
;     if (fresh_tid() == 0) {
;         __builtin_amdgcn_s_waitcnt(0);
;         const unsigned x = xb_xcc_id();
;         unsigned nloc = st[0], nx = st[1];
;         if (nloc == 0u) { xcd_barrier_complete(bar, x, nloc, nx); st[0] = nloc; st[1] = nx; }
.LBB0_935:
	s_waitcnt vmcnt(0)
	v_mov_b32_e32 v0, v250
	s_barrier
	s_getpc_b64 vcc
	v_mov_b32_e32 v2, vcc_lo
	v_mov_b32_e32 v3, vcc_hi
	v_lshlrev_b32_e32 v1, 6, v0
	v_min_u32_e32 v1, 0x6d80, v1
	v_cmp_lt_u32_e32 vcc, 63, v0
	s_and_saveexec_b64 s[4:5], vcc
	s_cbranch_execz .Lcpf_s10
	v_add_co_u32_e32 v2, vcc, v2, v1
	s_nop 1
	v_addc_co_u32_e32 v3, vcc, 0, v3, vcc
	global_load_dword v4, v[2:3], off
.Lcpf_s10:
	s_or_b64 exec, exec, s[4:5]
	s_nop 0
	v_cmp_eq_u32_e32 vcc, 0, v0
	s_and_saveexec_b64 s[4:5], vcc
	s_cbranch_execz .LBB0_987
	v_mov_b32_e32 v0, 0
	s_waitcnt vmcnt(0) expcnt(0) lgkmcnt(0)
	s_getreg_b32 s3, hwreg(HW_REG_XCC_ID, 0, 4)
	ds_read_b32 v2, v0
	ds_read_b32 v1, v0 offset:4
	s_and_b32 s3, s3, 15
	s_waitcnt lgkmcnt(1)
	v_cmp_ne_u32_e32 vcc, 0, v2
	s_cbranch_vccnz .LBB0_951
	s_add_u32 s6, s70, 0x34e2300
	s_addc_u32 s7, s71, 0
	s_add_u32 s8, s70, 0x34e2500
	s_addc_u32 s9, s71, 0
	s_add_u32 s10, s70, 0x34e2600
	s_addc_u32 s11, s71, 0
	s_add_u32 s12, s70, 0x34e2700
	s_addc_u32 s13, s71, 0
	s_add_u32 s14, s70, 0x34e2800
	s_addc_u32 s15, s71, 0
	s_add_u32 s16, s70, 0x34e2900
	s_addc_u32 s17, s71, 0
	s_add_u32 s18, s70, 0x34e2a00
	s_addc_u32 s19, s71, 0
	s_add_u32 s20, s70, 0x34e2b00
	s_addc_u32 s21, s71, 0
	s_add_u32 s22, s70, 0x34e2c00
	s_addc_u32 s23, s71, 0
	s_add_u32 s24, s70, 0x34e2d00
	s_addc_u32 s25, s71, 0
	s_add_u32 s26, s70, 0x34e2e00
	s_addc_u32 s27, s71, 0
	s_add_u32 s28, s70, 0x34e2f00
	s_addc_u32 s29, s71, 0
	s_add_u32 s30, s70, 0x34e3000
	s_addc_u32 s31, s71, 0
	s_add_u32 s34, s70, 0x34e3100
	s_addc_u32 s35, s71, 0
	s_add_u32 s36, s70, 0x34e3200
	s_addc_u32 s37, s71, 0
	s_add_u32 s38, s70, 0x34e3300
	s_addc_u32 s39, s71, 0
	s_add_u32 s40, s70, 0x34e3400
	s_addc_u32 s41, s71, 0
	s_mov_b32 s48, 1
	s_branch .LBB0_939

; DI float bf2f(unsigned short h) { return __uint_as_float(((unsigned)h) << 16); }
; DI void phase10(const Params& p) {
;     unsigned char* ws = p.ws;
;     int ft_ = threadIdx.x; asm volatile("" : "+v"(ft_));
;     const int lane = ft_ & 63, wid = ft_ >> 6;
;     const float* mod = (const float*)(ws + OFF_MOD);
;     const bf16_t* r1 = (const bf16_t*)(ws + 2 * U_);
;     float2* stats = (float2*)(ws + OFF_STATS);
;     bf16_t* h2 = (bf16_t*)(ws + 1 * U_);
;     for (int row0 = (blockIdx.x * 8 + wid) * 4; row0 < T_; row0 += gridDim.x * 32) {
;         float v[4][16];
; #pragma unroll
;         for (int rr = 0; rr < 4; ++rr)
; #pragma unroll
;             for (int i = 0; i < 4; ++i) { uint2 t = *(const uint2*)(r1 + (size_t)(row0 + rr) * 1024 + i * 256 + lane * 4); v[rr][4 * i] = bf2f(t.x & 0xffff); v[rr][4 * i + 1] = bf2f(t.x >> 16); v[rr][4 * i + 2] = bf2f(t.y & 0xffff); v[rr][4 * i + 3] = bf2f(t.y >> 16); }
.LBB0_987:
	s_or_b64 exec, exec, s[4:5]
	v_mov_b32_e32 v0, v250
	s_waitcnt lgkmcnt(0)
	s_waitcnt vmcnt(0)
	s_barrier
	v_readlane_b32 s84, v254, 32
	v_readlane_b32 s85, v254, 33
	v_readlane_b32 s86, v254, 34
	v_readlane_b32 s87, v254, 35
	v_lshlrev_b32_e32 v200, 4, v250
	v_and_b32_e32 v201, 0xff0, v200
	v_add_u32_e32 v202, 0x3000, v200
	v_add_u32_e32 v203, 0x9000, v200
	v_add_u32_e32 v204, 0xf000, v200
	v_add_u32_e32 v205, 0x15000, v200
	global_load_dwordx4 v[208:211], v201, s[84:85]
	global_load_dwordx4 v[212:215], v201, s[86:87]
	global_load_dwordx4 v[216:219], v202, s[50:51]
	global_load_dwordx4 v[220:223], v203, s[50:51]
	global_load_dwordx4 v[224:227], v204, s[50:51]
	global_load_dwordx4 v[228:231], v205, s[50:51]
	s_waitcnt vmcnt(0)
	ds_write_b128 v201, v[208:211] offset:1024
	ds_write_b128 v201, v[212:215] offset:5120
	ds_write_b128 v200, v[216:219] offset:9216
	ds_write_b128 v200, v[220:223] offset:17408
	ds_write_b128 v200, v[224:227] offset:25600
	ds_write_b128 v200, v[228:231] offset:33792
	s_waitcnt lgkmcnt(0)
	s_barrier
	v_readlane_b32 s3, v254, 52
	v_ashrrev_i32_e32 v1, 4, v0
	v_and_b32_e32 v1, -4, v1
	s_add_u32 s10, s70, 0x34e6100
	v_add_u32_e32 v4, s3, v1
	s_mov_b32 s3, 0x8000
	s_addc_u32 s11, s71, 0
	v_cmp_gt_i32_e32 vcc, s3, v4
	s_and_saveexec_b64 s[6:7], vcc
	s_cbranch_execz .LBB0_998
	v_readlane_b32 s12, v254, 20
	v_and_b32_e32 v1, 63, v0
	v_readlane_b32 s13, v254, 21
	v_readlane_b32 s14, v254, 22
	v_readlane_b32 s15, v254, 23
	v_readlane_b32 s24, v254, 32
	v_readlane_b32 s25, v254, 33
	v_lshlrev_b32_e32 v0, 2, v1
	v_mov_b32_e32 v7, 0
	v_readlane_b32 s4, v254, 56
	v_readlane_b32 s26, v254, 34
	v_readlane_b32 s27, v254, 35
	s_mov_b64 s[12:13], s[24:25]
	v_lshlrev_b32_e32 v6, 3, v1
	v_readlane_b32 s5, v254, 57
	v_or_b32_e32 v2, 0x100, v0
	v_or_b32_e32 v20, 0x200, v0
	v_or_b32_e32 v22, 0x300, v0
	v_lshlrev_b32_e32 v12, 4, v1
	v_mov_b32_e32 v13, v7
	v_readlane_b32 s16, v254, 24
	v_readlane_b32 s17, v254, 25
	v_readlane_b32 s18, v254, 26
	s_mov_b64 s[14:15], s[26:27]
	v_lshl_add_u64 v[8:9], s[4:5], 0, v[6:7]
	v_cmp_eq_u32_e32 vcc, 0, v1
	s_lshl_b32 s3, s33, 5
	v_lshl_add_u64 v[10:11], s[12:13], 0, v[12:13]
	v_lshl_add_u64 v[12:13], s[14:15], 0, v[12:13]
	v_lshl_add_u64 v[14:15], s[96:97], 0, v[6:7]
	s_mov_b64 s[8:9], 0
	s_mov_b32 s12, 0x3a800000
	v_mov_b32_e32 v16, 0x3727c5ac
	s_mov_b32 s13, 0x800000
	s_mov_b64 s[14:15], 0x3000
	s_mov_b64 s[16:17], 0x4000
	v_lshlrev_b32_e32 v6, 2, v0
	v_lshlrev_b32_e32 v18, 2, v2
	v_lshlrev_b32_e32 v20, 2, v20
	v_lshlrev_b32_e32 v22, 2, v22
	s_movk_i32 s18, 0x7fff
	v_readlane_b32 s19, v254, 27
	v_readlane_b32 s20, v254, 28
	v_readlane_b32 s21, v254, 29
	v_readlane_b32 s22, v254, 30
	v_readlane_b32 s23, v254, 31
	s_branch .LBB0_990

; DI int fresh_tid() { int t = threadIdx.x; asm volatile("" : "+v"(t)); return t; }
; DI unsigned xb_ld(unsigned* p)              { return __hip_atomic_load(p, __ATOMIC_RELAXED, __HIP_MEMORY_SCOPE_AGENT); }
; DI unsigned xb_xcc_id() { return (unsigned)__builtin_amdgcn_s_getreg((3 << 11) | 20) & 0xFu; }
; DI void xcd_barrier_complete(unsigned* bar, unsigned x, unsigned& nloc, unsigned& nx) {
;     ...
;     for (;;) {
;         sum = 0u; cnt = 0u; mine = 0u;
; #pragma unroll
;         for (unsigned j = 0; j < 16; ++j) { const unsigned c = xb_ld(&bar[XB_XCNT(j)]); sum += c; cnt += (c > 0u) ? 1u : 0u; mine = (j == x) ? c : mine; }
; DI void xcd_barrier(unsigned* bar, volatile __attribute__((address_space(3))) unsigned* st) {
;     asm volatile("s_waitcnt vmcnt(0)" ::: "memory");
;     __syncthreads();
;     if (fresh_tid() == 0) {
;         __builtin_amdgcn_s_waitcnt(0);
;         const unsigned x = xb_xcc_id();
;         unsigned nloc = st[0], nx = st[1];
;         if (nloc == 0u) { xcd_barrier_complete(bar, x, nloc, nx); st[0] = nloc; st[1] = nx; }
.LBB0_998:
	s_or_b64 exec, exec, s[6:7]
	s_waitcnt vmcnt(0)
	v_mov_b32_e32 v0, v250
	s_barrier
	s_getpc_b64 vcc
	v_mov_b32_e32 v2, vcc_lo
	v_mov_b32_e32 v3, vcc_hi
	v_lshlrev_b32_e32 v1, 6, v0
	v_min_u32_e32 v1, 0x5480, v1
	v_cmp_lt_u32_e32 vcc, 63, v0
	s_and_saveexec_b64 s[4:5], vcc
	s_cbranch_execz .Lcpf_s11
	v_add_co_u32_e32 v2, vcc, v2, v1
	s_nop 1
	v_addc_co_u32_e32 v3, vcc, 0, v3, vcc
	global_load_dword v4, v[2:3], off
.Lcpf_s11:
	s_or_b64 exec, exec, s[4:5]
	s_nop 0
	v_cmp_eq_u32_e32 vcc, 0, v0
	s_and_saveexec_b64 s[4:5], vcc
	v_readlane_b32 s12, v254, 20
	v_readlane_b32 s26, v254, 34
	v_readlane_b32 s27, v254, 35
	v_readlane_b32 s24, v254, 32
	v_readlane_b32 s25, v254, 33
	s_mov_b64 s[78:79], s[26:27]
	s_mov_b64 s[76:77], s[24:25]
	v_readlane_b32 s13, v254, 21
	v_readlane_b32 s14, v254, 22
	v_readlane_b32 s15, v254, 23
	v_readlane_b32 s16, v254, 24
	v_readlane_b32 s17, v254, 25
	v_readlane_b32 s18, v254, 26
	v_readlane_b32 s19, v254, 27
	v_readlane_b32 s20, v254, 28
	v_readlane_b32 s21, v254, 29
	v_readlane_b32 s22, v254, 30
	v_readlane_b32 s23, v254, 31
	s_cbranch_execz .LBB0_1050
	v_mov_b32_e32 v0, 0
	s_waitcnt vmcnt(0) expcnt(0) lgkmcnt(0)
	s_getreg_b32 s3, hwreg(HW_REG_XCC_ID, 0, 4)
	ds_read_b32 v2, v0
	ds_read_b32 v1, v0 offset:4
	s_and_b32 s3, s3, 15
	s_waitcnt lgkmcnt(1)
	v_cmp_ne_u32_e32 vcc, 0, v2
	s_cbranch_vccnz .LBB0_1014
	s_add_u32 s6, s70, 0x34e2300
	s_addc_u32 s7, s71, 0
	s_add_u32 s8, s70, 0x34e2500
	s_addc_u32 s9, s71, 0
	s_add_u32 s12, s70, 0x34e2600
	s_addc_u32 s13, s71, 0
	s_add_u32 s14, s70, 0x34e2700
	s_addc_u32 s15, s71, 0
	s_add_u32 s16, s70, 0x34e2800
	s_addc_u32 s17, s71, 0
	s_add_u32 s18, s70, 0x34e2900
	s_addc_u32 s19, s71, 0
	s_add_u32 s20, s70, 0x34e2a00
	s_addc_u32 s21, s71, 0
	s_add_u32 s22, s70, 0x34e2b00
	s_addc_u32 s23, s71, 0
	s_add_u32 s24, s70, 0x34e2c00
	s_addc_u32 s25, s71, 0
	s_add_u32 s26, s70, 0x34e2d00
	s_addc_u32 s27, s71, 0
	s_add_u32 s28, s70, 0x34e2e00
	s_addc_u32 s29, s71, 0
	s_add_u32 s30, s70, 0x34e2f00
	s_addc_u32 s31, s71, 0
	s_add_u32 s34, s70, 0x34e3000
	s_addc_u32 s35, s71, 0
	s_add_u32 s36, s70, 0x34e3100
	s_addc_u32 s37, s71, 0
	s_add_u32 s38, s70, 0x34e3200
	s_addc_u32 s39, s71, 0
	s_add_u32 s40, s70, 0x34e3300
	s_addc_u32 s41, s71, 0
	s_add_u32 s42, s70, 0x34e3400
	s_addc_u32 s43, s71, 0
	s_mov_b32 s50, 1
	s_branch .LBB0_1002

;     DI bool next(int i, Unit& u) const {
;         const long L = (long)i * G + c; if (L >= nwg) return false;
;         int wgid = (int)L; { const int q = nwg / NXCD, r = nwg % NXCD, xcd = wgid % NXCD, off = wgid / NXCD; wgid = (xcd < r ? xcd * (q + 1) : r * (q + 1) + (xcd - r) * q) + off; }
;         const int nig = WGM * nN, gid = wgid / nig, fm = gid * WGM, gsz = (nM - fm) < WGM ? (nM - fm) : WGM;
;         u.pm = fm + ((wgid % nig) % gsz); u.pn = (wgid % nig) / gsz; return true;
; __global__ void __launch_bounds__(512, 2) fwd_megakernel(Params p) {
;     ...
;     {
;         pg8::Gemm g{(const bf16_t*)(ws + 1 * U_), (const bf16_t*)(ws + OFF_WUP), 1024, 1024, 1024, 0};
;         S.init(T_, 5632, gridDim.x, blockIdx.x);
;         EpiUpF E{(bf16_t*)(ws + 4 * U_), p.in[25], p.in[26], p.out, p.out + HALO_ELEMS, p.out + 2 * HALO_ELEMS};
;         pg8::gemm_phase(glds, g, S, E);
.LBB0_1050:
	s_or_b64 exec, exec, s[4:5]
	v_mov_b32_e32 v8, v250
	s_cmpk_lt_i32 s2, 0xb00
	s_waitcnt lgkmcnt(0)
	s_waitcnt vmcnt(0)
	s_barrier
	s_cselect_b64 s[8:9], -1, 0
	s_cmpk_gt_i32 s2, 0xaff
	v_readfirstlane_b32 s20, v8
	s_cbranch_scc1 .LBB0_1052
	s_ashr_i32 s3, s2, 31
	s_lshr_b32 s3, s3, 29
	s_add_i32 s3, s2, s3
	s_ashr_i32 s4, s3, 3
	s_and_b32 s3, s3, -8
	s_sub_i32 s3, s2, s3
	s_cmp_lt_i32 s3, 0
	s_movk_i32 s5, 0x161
	s_cselect_b32 s5, s5, 0x160
	s_mul_i32 s3, s3, s5
	s_add_i32 s3, s3, s4
	s_mul_hi_i32 s4, s3, 0x2e8ba2e9
	s_lshr_b32 s5, s4, 31
	s_ashr_i32 s4, s4, 4
	s_add_i32 s4, s4, s5
	s_lshl_b32 s5, s4, 2
	s_mulk_i32 s4, 0x58
	s_sub_i32 s3, s3, s4
	s_bfe_i32 s4, s3, 0x80000
	s_bfe_u32 s4, s4, 0x2000d
	s_add_i32 s4, s3, s4
	s_bfe_i32 s6, s4, 0x80000
	s_and_b32 s4, s4, 0xfc
	s_sub_i32 s3, s3, s4
	s_sext_i32_i16 s6, s6
	s_sext_i32_i8 s3, s3
	s_add_i32 s4, s5, s3
	s_ashr_i32 s6, s6, 2

; DI int fresh_tid() { int t = threadIdx.x; asm volatile("" : "+v"(t)); return t; }
; DI unsigned xb_ld(unsigned* p)              { return __hip_atomic_load(p, __ATOMIC_RELAXED, __HIP_MEMORY_SCOPE_AGENT); }
; DI unsigned xb_xcc_id() { return (unsigned)__builtin_amdgcn_s_getreg((3 << 11) | 20) & 0xFu; }
; DI void xcd_barrier_complete(unsigned* bar, unsigned x, unsigned& nloc, unsigned& nx) {
;     ...
;     for (;;) {
;         sum = 0u; cnt = 0u; mine = 0u;
; #pragma unroll
;         for (unsigned j = 0; j < 16; ++j) { const unsigned c = xb_ld(&bar[XB_XCNT(j)]); sum += c; cnt += (c > 0u) ? 1u : 0u; mine = (j == x) ? c : mine; }
; DI void xcd_barrier(unsigned* bar, volatile __attribute__((address_space(3))) unsigned* st) {
;     asm volatile("s_waitcnt vmcnt(0)" ::: "memory");
;     __syncthreads();
;     if (fresh_tid() == 0) {
;         __builtin_amdgcn_s_waitcnt(0);
;         const unsigned x = xb_xcc_id();
;         unsigned nloc = st[0], nx = st[1];
;         if (nloc == 0u) { xcd_barrier_complete(bar, x, nloc, nx); st[0] = nloc; st[1] = nx; }
.LBB0_1092:
	s_waitcnt vmcnt(0)
	v_mov_b32_e32 v0, v250
	s_barrier
	s_getpc_b64 vcc
	v_mov_b32_e32 v2, vcc_lo
	v_mov_b32_e32 v3, vcc_hi
	v_lshlrev_b32_e32 v1, 6, v0
	v_min_u32_e32 v1, 0x3180, v1
	v_cmp_lt_u32_e32 vcc, 63, v0
	s_and_saveexec_b64 s[4:5], vcc
	s_cbranch_execz .Lcpf_s12
	v_add_co_u32_e32 v2, vcc, v2, v1
	s_nop 1
	v_addc_co_u32_e32 v3, vcc, 0, v3, vcc
	global_load_dword v4, v[2:3], off
.Lcpf_s12:
	s_or_b64 exec, exec, s[4:5]
	s_nop 0
	v_cmp_eq_u32_e32 vcc, 0, v0
	s_and_saveexec_b64 s[4:5], vcc
	s_cbranch_execz .LBB0_1144
	v_mov_b32_e32 v0, 0
	s_waitcnt vmcnt(0) expcnt(0) lgkmcnt(0)
	s_getreg_b32 s3, hwreg(HW_REG_XCC_ID, 0, 4)
	ds_read_b32 v2, v0
	ds_read_b32 v1, v0 offset:4
	s_and_b32 s3, s3, 15
	s_waitcnt lgkmcnt(1)
	v_cmp_ne_u32_e32 vcc, 0, v2
	s_cbranch_vccnz .LBB0_1108
	s_add_u32 s6, s70, 0x34e2300
	s_addc_u32 s7, s71, 0
	s_add_u32 s8, s70, 0x34e2500
	s_addc_u32 s9, s71, 0
	s_add_u32 s16, s70, 0x34e2600
	s_addc_u32 s17, s71, 0
	s_add_u32 s18, s70, 0x34e2700
	s_addc_u32 s19, s71, 0
	s_add_u32 s20, s70, 0x34e2800
	s_addc_u32 s21, s71, 0
	s_add_u32 s22, s70, 0x34e2900
	s_addc_u32 s23, s71, 0
	s_add_u32 s24, s70, 0x34e2a00
	s_addc_u32 s25, s71, 0
	s_add_u32 s26, s70, 0x34e2b00
	s_addc_u32 s27, s71, 0
	s_add_u32 s28, s70, 0x34e2c00
	s_addc_u32 s29, s71, 0
	s_add_u32 s30, s70, 0x34e2d00
	s_addc_u32 s31, s71, 0
	s_add_u32 s34, s70, 0x34e2e00
	s_addc_u32 s35, s71, 0
	s_add_u32 s36, s70, 0x34e2f00
	s_addc_u32 s37, s71, 0
	s_add_u32 s38, s70, 0x34e3000
	s_addc_u32 s39, s71, 0
	s_add_u32 s40, s70, 0x34e3100
	s_addc_u32 s41, s71, 0
	s_add_u32 s42, s70, 0x34e3200
	s_addc_u32 s43, s71, 0
	s_add_u32 s44, s70, 0x34e3300
	s_addc_u32 s45, s71, 0
	s_add_u32 s46, s70, 0x34e3400
	s_addc_u32 s47, s71, 0
	s_mov_b32 s54, 1
	s_branch .LBB0_1096

; DI int fresh_tid() { int t = threadIdx.x; asm volatile("" : "+v"(t)); return t; }
; DI void phase12(const Params& p) {
;     bf16_t* hid = (bf16_t*)(p.ws + 4 * U_);
;     const float* glast = p.out;
;     const float* gfirst = p.out + HALO_ELEMS;
;     const float* vfirst = p.out + 2 * HALO_ELEMS;
;     const float* cw = p.in[25];
;     const float* cb = p.in[26];
;     const int gtid = blockIdx.x * 512 + fresh_tid(), gstr = gridDim.x * 512;
;     for (int idx = gtid; idx < 512 * 2 * (FH / 4); idx += gstr) {
;         const int cgp = idx % (FH / 4), rr = (idx / (FH / 4)) & 1, wb = idx / (2 * (FH / 4));
.LBB0_1144:
	s_or_b64 exec, exec, s[4:5]
	v_mov_b32_e32 v0, v250
	v_readlane_b32 s3, v254, 53
	s_waitcnt lgkmcnt(0)
	s_waitcnt vmcnt(0)
	s_barrier
	s_nop 0
	v_add_u32_e32 v24, s3, v0
	s_mov_b32 s3, 0xb0000
	v_cmp_gt_i32_e32 vcc, s3, v24
	s_and_saveexec_b64 s[6:7], vcc
	s_cbranch_execz .LBB0_1151
	s_lshl_b32 s3, s33, 9
	s_add_u32 s8, s58, 0x2c00
	s_addc_u32 s9, s59, 0
	s_add_u32 s16, s58, 0x5800
	v_lshlrev_b32_e32 v0, 2, v0
	s_addc_u32 s17, s59, 0
	v_lshl_add_u32 v25, s2, 11, v0
	s_lshl_b32 s22, s33, 11
	s_mov_b64 s[18:19], 0
	s_mov_b32 s23, 0x2e8ba2e9
	s_movk_i32 s24, 0x1600
	s_mov_b32 s25, 0xaffff
	s_branch .LBB0_1147

; DI int fresh_tid() { int t = threadIdx.x; asm volatile("" : "+v"(t)); return t; }
; DI unsigned xb_ld(unsigned* p)              { return __hip_atomic_load(p, __ATOMIC_RELAXED, __HIP_MEMORY_SCOPE_AGENT); }
; DI unsigned xb_xcc_id() { return (unsigned)__builtin_amdgcn_s_getreg((3 << 11) | 20) & 0xFu; }
; DI void xcd_barrier_complete(unsigned* bar, unsigned x, unsigned& nloc, unsigned& nx) {
;     ...
;     for (;;) {
;         sum = 0u; cnt = 0u; mine = 0u;
; #pragma unroll
;         for (unsigned j = 0; j < 16; ++j) { const unsigned c = xb_ld(&bar[XB_XCNT(j)]); sum += c; cnt += (c > 0u) ? 1u : 0u; mine = (j == x) ? c : mine; }
; DI void xcd_barrier(unsigned* bar, volatile __attribute__((address_space(3))) unsigned* st) {
;     asm volatile("s_waitcnt vmcnt(0)" ::: "memory");
;     __syncthreads();
;     if (fresh_tid() == 0) {
;         __builtin_amdgcn_s_waitcnt(0);
;         const unsigned x = xb_xcc_id();
;         unsigned nloc = st[0], nx = st[1];
;         if (nloc == 0u) { xcd_barrier_complete(bar, x, nloc, nx); st[0] = nloc; st[1] = nx; }
.LBB0_1151:
	s_or_b64 exec, exec, s[6:7]
	s_waitcnt vmcnt(0)
	v_mov_b32_e32 v0, v250
	s_barrier
	s_getpc_b64 vcc
	v_mov_b32_e32 v2, vcc_lo
	v_mov_b32_e32 v3, vcc_hi
	v_lshlrev_b32_e32 v1, 6, v0
	v_min_u32_e32 v1, 0x29c0, v1
	v_cmp_lt_u32_e32 vcc, 63, v0
	s_and_saveexec_b64 s[4:5], vcc
	s_cbranch_execz .Lcpf_s13
	v_add_co_u32_e32 v2, vcc, v2, v1
	s_nop 1
	v_addc_co_u32_e32 v3, vcc, 0, v3, vcc
	global_load_dword v4, v[2:3], off
.Lcpf_s13:
	s_or_b64 exec, exec, s[4:5]
	s_nop 0
	v_cmp_eq_u32_e32 vcc, 0, v0
	s_and_saveexec_b64 s[4:5], vcc
	s_cbranch_execz .LBB0_1203
	v_mov_b32_e32 v0, 0
	s_waitcnt vmcnt(0) expcnt(0) lgkmcnt(0)
	s_getreg_b32 s3, hwreg(HW_REG_XCC_ID, 0, 4)
	ds_read_b32 v2, v0
	ds_read_b32 v1, v0 offset:4
	s_and_b32 s3, s3, 15
	s_waitcnt lgkmcnt(1)
	v_cmp_ne_u32_e32 vcc, 0, v2
	s_cbranch_vccnz .LBB0_1167
	s_add_u32 s6, s70, 0x34e2300
	s_addc_u32 s7, s71, 0
	s_add_u32 s8, s70, 0x34e2500
	s_addc_u32 s9, s71, 0
	s_add_u32 s12, s70, 0x34e2600
	s_addc_u32 s13, s71, 0
	s_add_u32 s14, s70, 0x34e2700
	s_addc_u32 s15, s71, 0
	s_add_u32 s16, s70, 0x34e2800
	s_addc_u32 s17, s71, 0
	s_add_u32 s18, s70, 0x34e2900
	s_addc_u32 s19, s71, 0
	s_add_u32 s20, s70, 0x34e2a00
	s_addc_u32 s21, s71, 0
	s_add_u32 s22, s70, 0x34e2b00
	s_addc_u32 s23, s71, 0
	s_add_u32 s24, s70, 0x34e2c00
	s_addc_u32 s25, s71, 0
	s_add_u32 s26, s70, 0x34e2d00
	s_addc_u32 s27, s71, 0
	s_add_u32 s28, s70, 0x34e2e00
	s_addc_u32 s29, s71, 0
	s_add_u32 s30, s70, 0x34e2f00
	s_addc_u32 s31, s71, 0
	s_add_u32 s34, s70, 0x34e3000
	s_addc_u32 s35, s71, 0
	s_add_u32 s36, s70, 0x34e3100
	s_addc_u32 s37, s71, 0
	s_add_u32 s38, s70, 0x34e3200
	s_addc_u32 s39, s71, 0
	s_add_u32 s40, s70, 0x34e3300
	s_addc_u32 s41, s71, 0
	s_add_u32 s42, s70, 0x34e3400
	s_addc_u32 s43, s71, 0
	s_mov_b32 s50, 1
	s_branch .LBB0_1155

;     DI bool next(int i, Unit& u) const {
;         const long L = (long)i * G + c; if (L >= nwg) return false;
;         int wgid = (int)L; { const int q = nwg / NXCD, r = nwg % NXCD, xcd = wgid % NXCD, off = wgid / NXCD; wgid = (xcd < r ? xcd * (q + 1) : r * (q + 1) + (xcd - r) * q) + off; }
;         const int nig = WGM * nN, gid = wgid / nig, fm = gid * WGM, gsz = (nM - fm) < WGM ? (nM - fm) : WGM;
;         u.pm = fm + ((wgid % nig) % gsz); u.pn = (wgid % nig) / gsz; return true;
; __global__ void __launch_bounds__(512, 2) fwd_megakernel(Params p) {
;     ...
;     {
;         pg8::Gemm g{(const bf16_t*)(ws + 4 * U_), (const bf16_t*)(ws + OFF_WFD), FH, FH, FH, 0};
;         S.init(T_, 1024, gridDim.x, blockIdx.x);
;         EpiRes2 E{(const bf16_t*)(ws + 2 * U_), (const float2*)(ws + OFF_STATS), p.in[22], p.in[23], (const float*)(ws + OFF_MOD) + 5120, (bf16_t*)(ws + 1 * U_)};
;         pg8::gemm_phase(glds, g, S, E);
.LBB0_1203:
	s_or_b64 exec, exec, s[4:5]
	v_mov_b32_e32 v8, v250
	s_waitcnt lgkmcnt(0)
	s_waitcnt vmcnt(0)
	s_barrier
	s_and_b64 vcc, exec, s[0:1]
	v_readfirstlane_b32 s4, v8
	s_cbranch_vccnz .LBB0_1231
	s_ashr_i32 s3, s2, 31
	s_lshr_b32 s0, s3, 29
	s_add_i32 s6, s2, s0
	s_and_b32 s0, s6, -8
	s_sub_i32 s7, s2, s0
	s_cmp_gt_i32 s7, -1
	s_cbranch_scc0 .LBB0_1206
	s_lshl_b32 s5, s7, 6
	s_ashr_i32 s6, s6, 3
	s_cbranch_execz .LBB0_1207
	s_branch .LBB0_1208

; DI int fresh_tid() { int t = threadIdx.x; asm volatile("" : "+v"(t)); return t; }
; DI unsigned xb_ld(unsigned* p)              { return __hip_atomic_load(p, __ATOMIC_RELAXED, __HIP_MEMORY_SCOPE_AGENT); }
; DI unsigned xb_xcc_id() { return (unsigned)__builtin_amdgcn_s_getreg((3 << 11) | 20) & 0xFu; }
; DI void xcd_barrier_complete(unsigned* bar, unsigned x, unsigned& nloc, unsigned& nx) {
;     ...
;     for (;;) {
;         sum = 0u; cnt = 0u; mine = 0u;
; #pragma unroll
;         for (unsigned j = 0; j < 16; ++j) { const unsigned c = xb_ld(&bar[XB_XCNT(j)]); sum += c; cnt += (c > 0u) ? 1u : 0u; mine = (j == x) ? c : mine; }
; DI void xcd_barrier(unsigned* bar, volatile __attribute__((address_space(3))) unsigned* st) {
;     asm volatile("s_waitcnt vmcnt(0)" ::: "memory");
;     __syncthreads();
;     if (fresh_tid() == 0) {
;         __builtin_amdgcn_s_waitcnt(0);
;         const unsigned x = xb_xcc_id();
;         unsigned nloc = st[0], nx = st[1];
;         if (nloc == 0u) { xcd_barrier_complete(bar, x, nloc, nx); st[0] = nloc; st[1] = nx; }
.LBB0_1231:
	s_waitcnt vmcnt(0)
	v_mov_b32_e32 v0, v250
	s_barrier
	s_getpc_b64 vcc
	v_mov_b32_e32 v2, vcc_lo
	v_mov_b32_e32 v3, vcc_hi
	v_lshlrev_b32_e32 v1, 6, v0
	v_min_u32_e32 v1, 0xe40, v1
	v_cmp_lt_u32_e32 vcc, 63, v0
	s_and_saveexec_b64 s[0:1], vcc
	s_cbranch_execz .Lcpf_s14
	v_add_co_u32_e32 v2, vcc, v2, v1
	s_nop 1
	v_addc_co_u32_e32 v3, vcc, 0, v3, vcc
	global_load_dword v4, v[2:3], off
.Lcpf_s14:
	s_or_b64 exec, exec, s[0:1]
	s_nop 0
	v_cmp_eq_u32_e32 vcc, 0, v0
	s_and_saveexec_b64 s[0:1], vcc
	s_cbranch_execz .LBB0_1283
	v_mov_b32_e32 v0, 0
	s_waitcnt vmcnt(0) expcnt(0) lgkmcnt(0)
	s_getreg_b32 s2, hwreg(HW_REG_XCC_ID, 0, 4)
	ds_read_b32 v2, v0
	ds_read_b32 v1, v0 offset:4
	s_and_b32 s44, s2, 15
	s_waitcnt lgkmcnt(1)
	v_cmp_ne_u32_e32 vcc, 0, v2
	s_cbranch_vccnz .LBB0_1247
	s_add_u32 s2, s70, 0x34e2300
	s_addc_u32 s3, s71, 0
	s_add_u32 s4, s70, 0x34e2500
	s_addc_u32 s5, s71, 0
	s_add_u32 s6, s70, 0x34e2600
	s_addc_u32 s7, s71, 0
	s_add_u32 s8, s70, 0x34e2700
	s_addc_u32 s9, s71, 0
	s_add_u32 s10, s70, 0x34e2800
	s_addc_u32 s11, s71, 0
	s_add_u32 s12, s70, 0x34e2900
	s_addc_u32 s13, s71, 0
	s_add_u32 s14, s70, 0x34e2a00
	s_addc_u32 s15, s71, 0
	s_add_u32 s16, s70, 0x34e2b00
	s_addc_u32 s17, s71, 0
	s_add_u32 s18, s70, 0x34e2c00
	s_addc_u32 s19, s71, 0
	s_add_u32 s20, s70, 0x34e2d00
	s_addc_u32 s21, s71, 0
	s_add_u32 s22, s70, 0x34e2e00
	s_addc_u32 s23, s71, 0
	s_add_u32 s24, s70, 0x34e2f00
	s_addc_u32 s25, s71, 0
	s_add_u32 s26, s70, 0x34e3000
	s_addc_u32 s27, s71, 0
	s_add_u32 s28, s70, 0x34e3100
	s_addc_u32 s29, s71, 0
	s_add_u32 s30, s70, 0x34e3200
	s_addc_u32 s31, s71, 0
	s_add_u32 s34, s70, 0x34e3300
	s_addc_u32 s35, s71, 0
	s_add_u32 s36, s70, 0x34e3400
	s_addc_u32 s37, s71, 0
	s_mov_b32 s45, 1
	s_branch .LBB0_1235

; DI float bf2f(unsigned short h) { return __uint_as_float(((unsigned)h) << 16); }
; DI void phase14(const Params& p) {
;     int ft_ = threadIdx.x; asm volatile("" : "+v"(ft_));
;     const int lane = ft_ & 63, wid = ft_ >> 6;
;     for (int row0 = (blockIdx.x * 8 + wid) * 4; row0 < T_; row0 += gridDim.x * 32) {
;         float v[4][16];
; #pragma unroll
;         for (int rr = 0; rr < 4; ++rr)
; #pragma unroll
;             for (int i = 0; i < 4; ++i) { uint2 t = *(const uint2*)((const bf16_t*)(p.ws + 1 * U_) + (size_t)(row0 + rr) * 1024 + i * 256 + lane * 4); v[rr][4 * i] = bf2f(t.x & 0xffff); v[rr][4 * i + 1] = bf2f(t.x >> 16); v[rr][4 * i + 2] = bf2f(t.y & 0xffff); v[rr][4 * i + 3] = bf2f(t.y >> 16); }
.LBB0_1283:
	s_or_b64 exec, exec, s[0:1]
	s_waitcnt lgkmcnt(0)
	s_waitcnt vmcnt(0)
	s_barrier
	v_readlane_b32 s0, v254, 52
	v_ashrrev_i32_e32 v0, 4, v250
	v_and_b32_e32 v0, -4, v0
	v_add_u32_e32 v8, s0, v0
	s_mov_b32 s0, 0x8000
	v_cmp_gt_i32_e32 vcc, s0, v8
	s_and_saveexec_b64 s[0:1], vcc
	s_cbranch_execz .LBB0_1286
	v_lshlrev_b32_e32 v0, 2, v250
	v_and_b32_e32 v2, 0xfc, v0
	v_lshlrev_b32_e32 v0, 1, v2
	v_mov_b32_e32 v1, 0
	v_lshl_add_u64 v[10:11], s[96:97], 0, v[0:1]
	v_lshlrev_b32_e32 v0, 2, v2
	s_mov_b32 s4, 0x3727c5ac
	s_lshl_b32 s3, s33, 5
	v_lshl_add_u64 v[12:13], s[64:65], 0, v[0:1]
	v_lshl_add_u64 v[14:15], s[66:67], 0, v[0:1]
	v_lshl_add_u64 v[16:17], s[68:69], 0, v[0:1]
	s_mov_b64 s[0:1], 0
	s_mov_b32 s2, 0x3a800000
	v_mov_b64_e32 v[18:19], s[4:5]
	s_mov_b32 s4, 0x800000
	s_movk_i32 s5, 0x7fff
